# v51 + LRU scan via in-place DPP fmac (no LDS shuffles) + flat_load/flat_store -> global_load/global_store in the z/GLU/MLP1 epilogues
# speedup vs baseline: 1.0074x; 1.0074x over previous
; __device__ __forceinline__ unsigned cvt_pk_bf16(float lo, float hi) { unsigned r; asm volatile("v_cvt_pk_bf16_f32 %0, %1, %2" : "=v"(r) : "v"(lo), "v"(hi)); return r; }
; #define PG8_OPQ(p) asm volatile("" : "+v"(p))
;     __device__ __forceinline__ void operator()(const f32x4 (&acc)[2][2][4][2], const Unit& u, int wr, int wc, int fr, int fq) const {
;         char* p = (char*)(O + (size_t)(wr * 64 + fr) * ldc + u.pn * BM + wc * 32 + 8 * fq);
;         const size_t step = (size_t)16 * ldc * 2;
; #pragma unroll
;         for (int ai = 0; ai < 2; ++ai) {
; #pragma unroll
;             for (int m = 0; m < 4; ++m) {
;                 PG8_OPQ(p);
; #pragma unroll
;                 for (int bj = 0; bj < 2; ++bj) { f32x4 v0 = acc[ai][bj][m][0], v1 = acc[ai][bj][m][1];
;                     if (ACT == 1) {
; #pragma unroll
;                         for (int j = 0; j < 4; ++j) { const float a0 = fmaxf(v0[j], 0.f), a1 = fmaxf(v1[j], 0.f); v0[j] = a0 * a0; v1[j] = a1 * a1; } }
;                     u32x4 w; w.x = cvt_pk_bf16(v0[0], v0[1]); w.y = cvt_pk_bf16(v0[2], v0[3]); w.z = cvt_pk_bf16(v1[0], v1[1]); w.w = cvt_pk_bf16(v1[2], v1[3]);
;                     *(u32x4*)(p + bj * HALF * 2) = w; }
;                 p += step;
;             }
;             p += 4 * step;
;         }
;     }
.LBB0_134:
	s_lshl_b32 s36, s8, 8
	v_lshl_add_u64 v[144:145], s[36:37], 1, v[136:137]
	v_cvt_pk_bf16_f32 v122, v122, v123
	v_cvt_pk_bf16_f32 v123, v124, v125
	v_cvt_pk_bf16_f32 v124, v126, v127
	v_cvt_pk_bf16_f32 v125, v128, v129
	global_store_dwordx4 v[144:145], v[122:125], off
	v_cvt_pk_bf16_f32 v118, v118, v119
	v_cvt_pk_bf16_f32 v119, v120, v121
	v_cvt_pk_bf16_f32 v120, v114, v115
	v_lshl_add_u64 v[114:115], v[144:145], 0, s[12:13]
	v_cvt_pk_bf16_f32 v121, v116, v117
	global_store_dwordx4 v[144:145], v[118:121], off offset:256
	v_cvt_pk_bf16_f32 v110, v110, v111
	v_cvt_pk_bf16_f32 v111, v112, v113
	v_cvt_pk_bf16_f32 v112, v106, v107
	v_cvt_pk_bf16_f32 v113, v108, v109
	global_store_dwordx4 v[114:115], v[110:113], off
	v_cvt_pk_bf16_f32 v102, v102, v103
	v_cvt_pk_bf16_f32 v103, v104, v105
	v_cvt_pk_bf16_f32 v104, v98, v99
	v_lshl_add_u64 v[98:99], v[114:115], 0, s[12:13]
	v_cvt_pk_bf16_f32 v105, v100, v101
	global_store_dwordx4 v[114:115], v[102:105], off offset:256
	v_cvt_pk_bf16_f32 v94, v94, v95
	v_cvt_pk_bf16_f32 v95, v96, v97
	v_cvt_pk_bf16_f32 v96, v90, v91
	v_cvt_pk_bf16_f32 v97, v92, v93
	global_store_dwordx4 v[98:99], v[94:97], off
	v_cvt_pk_bf16_f32 v86, v86, v87
	v_cvt_pk_bf16_f32 v87, v88, v89
	v_cvt_pk_bf16_f32 v88, v82, v83
	v_lshl_add_u64 v[82:83], v[98:99], 0, s[12:13]
	s_mov_b64 s[46:47], 0x64000
	v_cvt_pk_bf16_f32 v89, v84, v85
	global_store_dwordx4 v[98:99], v[86:89], off offset:256
	v_cvt_pk_bf16_f32 v78, v78, v79
	v_cvt_pk_bf16_f32 v79, v80, v81
	v_cvt_pk_bf16_f32 v80, v74, v75
	v_cvt_pk_bf16_f32 v81, v76, v77
	global_store_dwordx4 v[82:83], v[78:81], off
	v_cvt_pk_bf16_f32 v70, v70, v71
	v_cvt_pk_bf16_f32 v71, v72, v73
	v_cvt_pk_bf16_f32 v72, v66, v67
	v_lshl_add_u64 v[66:67], v[82:83], 0, s[46:47]
	v_cvt_pk_bf16_f32 v73, v68, v69
	global_store_dwordx4 v[82:83], v[70:73], off offset:256
	v_cvt_pk_bf16_f32 v62, v62, v63
	v_cvt_pk_bf16_f32 v63, v64, v65
	v_cvt_pk_bf16_f32 v64, v58, v59
	v_cvt_pk_bf16_f32 v65, v60, v61
	global_store_dwordx4 v[66:67], v[62:65], off
	v_cvt_pk_bf16_f32 v54, v54, v55
	v_cvt_pk_bf16_f32 v55, v56, v57
	v_cvt_pk_bf16_f32 v56, v50, v51
	v_lshl_add_u64 v[50:51], v[66:67], 0, s[12:13]
	v_cvt_pk_bf16_f32 v57, v52, v53
	global_store_dwordx4 v[66:67], v[54:57], off offset:256
	v_cvt_pk_bf16_f32 v46, v46, v47
	v_cvt_pk_bf16_f32 v47, v48, v49
	v_cvt_pk_bf16_f32 v48, v42, v43
	v_cvt_pk_bf16_f32 v49, v44, v45
	global_store_dwordx4 v[50:51], v[46:49], off
	v_cvt_pk_bf16_f32 v38, v38, v39
	v_cvt_pk_bf16_f32 v39, v40, v41
	v_cvt_pk_bf16_f32 v40, v34, v35
	v_lshl_add_u64 v[34:35], v[50:51], 0, s[12:13]
	v_cvt_pk_bf16_f32 v41, v36, v37
	global_store_dwordx4 v[50:51], v[38:41], off offset:256
	v_cvt_pk_bf16_f32 v30, v30, v31
	v_cvt_pk_bf16_f32 v31, v32, v33
	v_cvt_pk_bf16_f32 v32, v26, v27
	v_cvt_pk_bf16_f32 v33, v28, v29
	global_store_dwordx4 v[34:35], v[30:33], off
	v_cvt_pk_bf16_f32 v22, v22, v23
	v_cvt_pk_bf16_f32 v23, v24, v25
	v_cvt_pk_bf16_f32 v24, v18, v19
	v_lshl_add_u64 v[18:19], v[34:35], 0, s[12:13]
	s_cmp_eq_u32 s8, 8
	s_mov_b64 s[8:9], -1
	v_cvt_pk_bf16_f32 v25, v20, v21
	global_store_dwordx4 v[34:35], v[22:25], off offset:256
	v_cvt_pk_bf16_f32 v14, v14, v15
	v_cvt_pk_bf16_f32 v15, v16, v17
	v_cvt_pk_bf16_f32 v16, v10, v11
	v_cvt_pk_bf16_f32 v17, v12, v13
	global_store_dwordx4 v[18:19], v[14:17], off
	v_cvt_pk_bf16_f32 v6, v6, v7
	v_cvt_pk_bf16_f32 v7, v8, v9
	v_cvt_pk_bf16_f32 v8, v2, v3
	v_cvt_pk_bf16_f32 v9, v4, v5
	global_store_dwordx4 v[18:19], v[6:9], off offset:256
	s_cbranch_scc1 .LBB0_126
	s_andn2_b64 vcc, exec, s[26:27]
	s_cbranch_vccnz .LBB0_125
	s_barrier
	s_branch .LBB0_125

; __device__ __forceinline__ float fexp(float x) { return __builtin_amdgcn_exp2f(x * 1.4426950408889634f); }
; __device__ __forceinline__ float bflo_(unsigned w) { return __uint_as_float(w << 16); }
; __device__ __forceinline__ float bfhi_(unsigned w) { return __uint_as_float(w & 0xffff0000u); }
; __device__ __forceinline__ unsigned cvt_pk_bf16(float lo, float hi) { unsigned r; asm volatile("v_cvt_pk_bf16_f32 %0, %1, %2" : "=v"(r) : "v"(lo), "v"(hi)); return r; }
; #define PG8_OPQ(p) asm volatile("" : "+v"(p))
;     __device__ __forceinline__ void operator()(const f32x4 (&acc)[2][2][4][2], const Unit& u, int wr, int wc, int fr, int fq) const {
;         const int col0 = u.pn * BM + wc * 32 + 8 * fq;
;         const char* py = (const char*)(Y + (size_t)(wr * 64 + fr) * ldy + col0);
;         char* po = (char*)(O + (size_t)(wr * 64 + fr) * ldc + col0);
;         const size_t sy = (size_t)16 * ldy * 2, so = (size_t)16 * ldc * 2;
; #pragma unroll
;         for (int ai = 0; ai < 2; ++ai) {
;             PG8_OPQ(py); PG8_OPQ(po);
;             u32x4 yv[4][2];
; #pragma unroll
;             for (int m = 0; m < 4; ++m)
; #pragma unroll
;                 for (int bj = 0; bj < 2; ++bj) yv[m][bj] = *(const u32x4*)(py + m * sy + bj * HALF * 2);
;             asm volatile("" ::: "memory");
; #pragma unroll
;             for (int m = 0; m < 4; ++m)
; #pragma unroll
;                 for (int bj = 0; bj < 2; ++bj) { const f32x4 v0 = acc[ai][bj][m][0], v1 = acc[ai][bj][m][1]; const u32x4 y = yv[m][bj];
;                     u32x4 w;
;                     w.x = cvt_pk_bf16(bflo_(y.x) * __builtin_amdgcn_rcpf(1.f + fexp(-v0[0])), bfhi_(y.x) * __builtin_amdgcn_rcpf(1.f + fexp(-v0[1])));
;                     w.y = cvt_pk_bf16(bflo_(y.y) * __builtin_amdgcn_rcpf(1.f + fexp(-v0[2])), bfhi_(y.y) * __builtin_amdgcn_rcpf(1.f + fexp(-v0[3])));
;                     w.z = cvt_pk_bf16(bflo_(y.z) * __builtin_amdgcn_rcpf(1.f + fexp(-v1[0])), bfhi_(y.z) * __builtin_amdgcn_rcpf(1.f + fexp(-v1[1])));
;                     w.w = cvt_pk_bf16(bflo_(y.w) * __builtin_amdgcn_rcpf(1.f + fexp(-v1[2])), bfhi_(y.w) * __builtin_amdgcn_rcpf(1.f + fexp(-v1[3])));
;                     *(u32x4*)(po + m * so + bj * HALF * 2) = w; }
.LBB0_409:
	v_ashrrev_i32_e32 v107, 31, v106
	v_or_b32_e32 v0, s5, v134
	v_lshlrev_b64 v[108:109], 9, v[106:107]
	v_lshlrev_b64 v[106:107], 11, v[106:107]
	v_lshl_add_u64 v[108:109], s[10:11], 0, v[108:109]
	v_lshlrev_b32_e32 v0, 1, v0
	v_lshl_add_u64 v[106:107], s[2:3], 0, v[106:107]
	v_lshl_add_u64 v[162:163], v[108:109], 0, v[0:1]
	v_lshl_add_u64 v[106:107], v[106:107], 0, v[0:1]
	s_mov_b64 s[2:3], 0x140000
	v_lshl_add_u64 v[164:165], v[106:107], 0, s[2:3]
	global_load_dwordx4 v[158:161], v[162:163], off
	global_load_dwordx4 v[154:157], v[162:163], off offset:256
	v_add_co_u32_e32 v106, vcc, s1, v162
	v_mul_f32_e32 v142, 0xbfb8aa3b, v142
	s_nop 0
	v_addc_co_u32_e32 v107, vcc, 0, v163, vcc
	global_load_dwordx4 v[150:153], v[106:107], off
	global_load_dwordx4 v[146:149], v[106:107], off offset:256
	v_exp_f32_e32 v142, v142
	v_mul_f32_e32 v143, 0xbfb8aa3b, v143
	v_exp_f32_e32 v143, v143
	v_mul_f32_e32 v138, 0xbfb8aa3b, v138
	v_add_f32_e32 v142, 1.0, v142
	v_rcp_f32_e32 v142, v142
	v_add_f32_e32 v143, 1.0, v143
	v_rcp_f32_e32 v143, v143
	v_exp_f32_e32 v138, v138
	v_mul_f32_e32 v139, 0xbfb8aa3b, v139
	v_add_co_u32_e32 v106, vcc, s4, v162
	v_exp_f32_e32 v139, v139
	s_nop 0
	v_addc_co_u32_e32 v107, vcc, 0, v163, vcc
	global_load_dwordx4 v[134:137], v[106:107], off
	global_load_dwordx4 v[130:133], v[106:107], off offset:256
	v_add_co_u32_e32 v106, vcc, s8, v162
	v_add_f32_e32 v138, 1.0, v138
	s_nop 0
	v_addc_co_u32_e32 v107, vcc, 0, v163, vcc
	global_load_dwordx4 v[118:121], v[106:107], off
	s_nop 0
	global_load_dwordx4 v[106:109], v[106:107], off offset:256
	v_rcp_f32_e32 v138, v138
	v_add_f32_e32 v139, 1.0, v139
	v_rcp_f32_e32 v139, v139
	v_mul_f32_e32 v126, 0xbfb8aa3b, v126
	v_exp_f32_e32 v126, v126
	v_mul_f32_e32 v127, 0xbfb8aa3b, v127
	v_exp_f32_e32 v127, v127
	v_mul_f32_e32 v122, 0xbfb8aa3b, v122
	v_add_f32_e32 v126, 1.0, v126
	v_rcp_f32_e32 v126, v126
	v_add_f32_e32 v127, 1.0, v127
	v_rcp_f32_e32 v127, v127
	v_exp_f32_e32 v122, v122
	v_mul_f32_e32 v123, 0xbfb8aa3b, v123
	v_exp_f32_e32 v123, v123
	v_mul_f32_e32 v114, 0xbfb8aa3b, v114
	v_add_f32_e32 v122, 1.0, v122
	v_rcp_f32_e32 v122, v122
	v_add_f32_e32 v123, 1.0, v123
	v_rcp_f32_e32 v123, v123
	v_exp_f32_e32 v114, v114
	v_mul_f32_e32 v115, 0xbfb8aa3b, v115
	v_exp_f32_e32 v115, v115
	v_mul_f32_e32 v110, 0xbfb8aa3b, v110
	v_add_f32_e32 v114, 1.0, v114
	v_rcp_f32_e32 v114, v114
	v_add_f32_e32 v115, 1.0, v115
	v_rcp_f32_e32 v115, v115
	v_exp_f32_e32 v110, v110
	v_mul_f32_e32 v111, 0xbfb8aa3b, v111
	v_exp_f32_e32 v111, v111
	v_mul_f32_e32 v102, 0xbfb8aa3b, v102
	v_add_f32_e32 v110, 1.0, v110
	v_rcp_f32_e32 v110, v110
	v_add_f32_e32 v111, 1.0, v111
	v_rcp_f32_e32 v111, v111
	v_exp_f32_e32 v102, v102
	v_mul_f32_e32 v103, 0xbfb8aa3b, v103
	v_exp_f32_e32 v103, v103
	v_mul_f32_e32 v98, 0xbfb8aa3b, v98
	v_add_f32_e32 v102, 1.0, v102
	v_rcp_f32_e32 v102, v102
	v_add_f32_e32 v103, 1.0, v103
	v_rcp_f32_e32 v103, v103
	v_exp_f32_e32 v98, v98
	v_mul_f32_e32 v99, 0xbfb8aa3b, v99
	v_exp_f32_e32 v99, v99
	v_mul_f32_e32 v94, 0xbfb8aa3b, v94
	v_add_f32_e32 v98, 1.0, v98
	s_waitcnt vmcnt(0) lgkmcnt(0)
	v_lshlrev_b32_e32 v0, 16, v158
	v_mul_f32_e32 v0, v142, v0
	v_and_b32_e32 v142, 0xffff0000, v158
	v_mul_f32_e32 v142, v143, v142
	v_mul_f32_e32 v143, 0xbfb8aa3b, v144
	v_exp_f32_e32 v143, v143
	v_mul_f32_e32 v144, 0xbfb8aa3b, v145
	v_exp_f32_e32 v144, v144
	v_cvt_pk_bf16_f32 v142, v0, v142
	v_add_f32_e32 v143, 1.0, v143
	v_rcp_f32_e32 v143, v143
	v_add_f32_e32 v144, 1.0, v144
	v_rcp_f32_e32 v144, v144
	v_lshlrev_b32_e32 v0, 16, v159
	v_mul_f32_e32 v0, v143, v0
	v_and_b32_e32 v143, 0xffff0000, v159
	v_mul_f32_e32 v143, v144, v143
	v_cvt_pk_bf16_f32 v143, v0, v143
	v_lshlrev_b32_e32 v0, 16, v160
	v_mul_f32_e32 v0, v138, v0
	v_and_b32_e32 v138, 0xffff0000, v160
	v_mul_f32_e32 v138, v139, v138
	v_cvt_pk_bf16_f32 v144, v0, v138
	v_mul_f32_e32 v138, 0xbfb8aa3b, v140
	v_exp_f32_e32 v138, v138
	v_mul_f32_e32 v139, 0xbfb8aa3b, v141
	v_exp_f32_e32 v139, v139
	v_lshlrev_b32_e32 v0, 16, v161
	v_add_f32_e32 v138, 1.0, v138
	v_rcp_f32_e32 v138, v138
	v_add_f32_e32 v139, 1.0, v139
	v_rcp_f32_e32 v139, v139
	v_rcp_f32_e32 v98, v98
	v_mul_f32_e32 v0, v138, v0
	v_and_b32_e32 v138, 0xffff0000, v161
	v_mul_f32_e32 v138, v139, v138
	v_cvt_pk_bf16_f32 v145, v0, v138
	v_lshlrev_b32_e32 v0, 16, v154
	v_mul_f32_e32 v0, v126, v0
	v_and_b32_e32 v126, 0xffff0000, v154
	v_mul_f32_e32 v126, v127, v126
	v_mul_f32_e32 v127, 0xbfb8aa3b, v128
	v_exp_f32_e32 v127, v127
	v_mul_f32_e32 v128, 0xbfb8aa3b, v129
	v_exp_f32_e32 v128, v128
	global_store_dwordx4 v[164:165], v[142:145], off
	v_add_f32_e32 v127, 1.0, v127
	v_rcp_f32_e32 v127, v127
	v_add_f32_e32 v128, 1.0, v128
	v_rcp_f32_e32 v128, v128
	v_cvt_pk_bf16_f32 v126, v0, v126
	v_lshlrev_b32_e32 v0, 16, v155
	v_mul_f32_e32 v0, v127, v0
	v_and_b32_e32 v127, 0xffff0000, v155
	v_mul_f32_e32 v127, v128, v127
	v_cvt_pk_bf16_f32 v127, v0, v127
	v_lshlrev_b32_e32 v0, 16, v156
	v_mul_f32_e32 v0, v122, v0
	v_and_b32_e32 v122, 0xffff0000, v156
	v_mul_f32_e32 v122, v123, v122
	v_cvt_pk_bf16_f32 v128, v0, v122
	v_mul_f32_e32 v122, 0xbfb8aa3b, v124
	v_exp_f32_e32 v122, v122
	v_mul_f32_e32 v123, 0xbfb8aa3b, v125
	v_exp_f32_e32 v123, v123
	v_lshlrev_b32_e32 v0, 16, v157
	v_add_f32_e32 v122, 1.0, v122
	v_rcp_f32_e32 v122, v122
	v_add_f32_e32 v123, 1.0, v123
	v_rcp_f32_e32 v123, v123
	v_add_f32_e32 v99, 1.0, v99
	v_mul_f32_e32 v0, v122, v0
	v_and_b32_e32 v122, 0xffff0000, v157
	v_mul_f32_e32 v122, v123, v122
	v_cvt_pk_bf16_f32 v129, v0, v122
	v_lshlrev_b32_e32 v0, 16, v150
	v_mul_f32_e32 v0, v114, v0
	v_and_b32_e32 v114, 0xffff0000, v150
	v_mul_f32_e32 v114, v115, v114
	v_mul_f32_e32 v115, 0xbfb8aa3b, v116
; __device__ __forceinline__ float fexp(float x) { return __builtin_amdgcn_exp2f(x * 1.4426950408889634f); }
; __device__ __forceinline__ float bflo_(unsigned w) { return __uint_as_float(w << 16); }
; __device__ __forceinline__ float bfhi_(unsigned w) { return __uint_as_float(w & 0xffff0000u); }
; __device__ __forceinline__ unsigned cvt_pk_bf16(float lo, float hi) { unsigned r; asm volatile("v_cvt_pk_bf16_f32 %0, %1, %2" : "=v"(r) : "v"(lo), "v"(hi)); return r; }
;     __device__ __forceinline__ void operator()(const f32x4 (&acc)[2][2][4][2], const Unit& u, int wr, int wc, int fr, int fq) const {
;     ...
;             for (int m = 0; m < 4; ++m)
; #pragma unroll
;                 for (int bj = 0; bj < 2; ++bj) yv[m][bj] = *(const u32x4*)(py + m * sy + bj * HALF * 2);
;             asm volatile("" ::: "memory");
; #pragma unroll
;             for (int m = 0; m < 4; ++m)
; #pragma unroll
;                 for (int bj = 0; bj < 2; ++bj) { const f32x4 v0 = acc[ai][bj][m][0], v1 = acc[ai][bj][m][1]; const u32x4 y = yv[m][bj];
;                     u32x4 w;
;                     w.x = cvt_pk_bf16(bflo_(y.x) * __builtin_amdgcn_rcpf(1.f + fexp(-v0[0])), bfhi_(y.x) * __builtin_amdgcn_rcpf(1.f + fexp(-v0[1])));
;                     w.y = cvt_pk_bf16(bflo_(y.y) * __builtin_amdgcn_rcpf(1.f + fexp(-v0[2])), bfhi_(y.y) * __builtin_amdgcn_rcpf(1.f + fexp(-v0[3])));
;                     w.z = cvt_pk_bf16(bflo_(y.z) * __builtin_amdgcn_rcpf(1.f + fexp(-v1[0])), bfhi_(y.z) * __builtin_amdgcn_rcpf(1.f + fexp(-v1[1])));
;                     w.w = cvt_pk_bf16(bflo_(y.w) * __builtin_amdgcn_rcpf(1.f + fexp(-v1[2])), bfhi_(y.w) * __builtin_amdgcn_rcpf(1.f + fexp(-v1[3])));
;                     *(u32x4*)(po + m * so + bj * HALF * 2) = w; }
;             py += 8 * sy; po += 8 * so;
	v_exp_f32_e32 v115, v115
	v_mul_f32_e32 v116, 0xbfb8aa3b, v117
	v_exp_f32_e32 v116, v116
	global_store_dwordx4 v[164:165], v[126:129], off offset:256
	v_add_f32_e32 v115, 1.0, v115
	v_rcp_f32_e32 v115, v115
	v_add_f32_e32 v116, 1.0, v116
	v_rcp_f32_e32 v116, v116
	v_cvt_pk_bf16_f32 v114, v0, v114
	v_lshlrev_b32_e32 v0, 16, v151
	v_mul_f32_e32 v0, v115, v0
	v_and_b32_e32 v115, 0xffff0000, v151
	v_mul_f32_e32 v115, v116, v115
	v_cvt_pk_bf16_f32 v115, v0, v115
	v_lshlrev_b32_e32 v0, 16, v152
	v_mul_f32_e32 v0, v110, v0
	v_and_b32_e32 v110, 0xffff0000, v152
	v_mul_f32_e32 v110, v111, v110
	v_cvt_pk_bf16_f32 v116, v0, v110
	v_mul_f32_e32 v110, 0xbfb8aa3b, v112
	v_exp_f32_e32 v110, v110
	v_mul_f32_e32 v111, 0xbfb8aa3b, v113
	v_exp_f32_e32 v111, v111
	v_lshlrev_b32_e32 v0, 16, v153
	v_add_f32_e32 v110, 1.0, v110
	v_rcp_f32_e32 v110, v110
	v_add_f32_e32 v111, 1.0, v111
	v_rcp_f32_e32 v111, v111
	v_rcp_f32_e32 v99, v99
	v_mul_f32_e32 v0, v110, v0
	v_and_b32_e32 v110, 0xffff0000, v153
	v_mul_f32_e32 v110, v111, v110
	v_cvt_pk_bf16_f32 v117, v0, v110
	v_lshlrev_b32_e32 v0, 16, v146
	v_mul_f32_e32 v0, v102, v0
	v_and_b32_e32 v102, 0xffff0000, v146
	v_mul_f32_e32 v102, v103, v102
	v_mul_f32_e32 v103, 0xbfb8aa3b, v104
	v_exp_f32_e32 v103, v103
	v_mul_f32_e32 v104, 0xbfb8aa3b, v105
	v_exp_f32_e32 v104, v104
	v_add_co_u32_e32 v110, vcc, s87, v164
	v_add_f32_e32 v103, 1.0, v103
	v_rcp_f32_e32 v103, v103
	v_add_f32_e32 v104, 1.0, v104
	v_rcp_f32_e32 v104, v104
	v_addc_co_u32_e32 v111, vcc, 0, v165, vcc
	global_store_dwordx4 v[110:111], v[114:117], off
	v_cvt_pk_bf16_f32 v102, v0, v102
	v_lshlrev_b32_e32 v0, 16, v147
	v_mul_f32_e32 v0, v103, v0
	v_and_b32_e32 v103, 0xffff0000, v147
	v_mul_f32_e32 v103, v104, v103
	v_cvt_pk_bf16_f32 v103, v0, v103
	v_lshlrev_b32_e32 v0, 16, v148
	v_mul_f32_e32 v0, v98, v0
	v_and_b32_e32 v98, 0xffff0000, v148
	v_mul_f32_e32 v98, v99, v98
	v_cvt_pk_bf16_f32 v104, v0, v98
	v_mul_f32_e32 v98, 0xbfb8aa3b, v100
	v_exp_f32_e32 v98, v98
	v_mul_f32_e32 v99, 0xbfb8aa3b, v101
	v_exp_f32_e32 v99, v99
	v_exp_f32_e32 v94, v94
	v_mul_f32_e32 v95, 0xbfb8aa3b, v95
	v_exp_f32_e32 v95, v95
	v_add_f32_e32 v98, 1.0, v98
	v_rcp_f32_e32 v98, v98
	v_add_f32_e32 v99, 1.0, v99
	v_rcp_f32_e32 v99, v99
	v_add_f32_e32 v94, 1.0, v94
	v_rcp_f32_e32 v94, v94
	v_add_f32_e32 v95, 1.0, v95
	v_lshlrev_b32_e32 v0, 16, v149
	v_rcp_f32_e32 v95, v95
	v_mul_f32_e32 v0, v98, v0
	v_and_b32_e32 v98, 0xffff0000, v149
	v_mul_f32_e32 v98, v99, v98
	v_cvt_pk_bf16_f32 v105, v0, v98
	v_lshlrev_b32_e32 v0, 16, v134
	v_mul_f32_e32 v0, v94, v0
	v_and_b32_e32 v94, 0xffff0000, v134
	v_mul_f32_e32 v94, v95, v94
	v_mul_f32_e32 v95, 0xbfb8aa3b, v96
	v_exp_f32_e32 v95, v95
	v_mul_f32_e32 v96, 0xbfb8aa3b, v97
	v_exp_f32_e32 v96, v96
	v_mul_f32_e32 v90, 0xbfb8aa3b, v90
	v_exp_f32_e32 v90, v90
	v_mul_f32_e32 v91, 0xbfb8aa3b, v91
	v_add_f32_e32 v95, 1.0, v95
	v_exp_f32_e32 v91, v91
	v_rcp_f32_e32 v95, v95
	v_add_f32_e32 v96, 1.0, v96
	v_rcp_f32_e32 v96, v96
	v_add_f32_e32 v90, 1.0, v90
	global_store_dwordx4 v[110:111], v[102:105], off offset:256
	v_cvt_pk_bf16_f32 v94, v0, v94
	v_lshlrev_b32_e32 v0, 16, v135
	v_rcp_f32_e32 v90, v90
	v_add_f32_e32 v91, 1.0, v91
	v_mul_f32_e32 v0, v95, v0
	v_and_b32_e32 v95, 0xffff0000, v135
	v_rcp_f32_e32 v91, v91
	v_mul_f32_e32 v95, v96, v95
	v_cvt_pk_bf16_f32 v95, v0, v95
	v_lshlrev_b32_e32 v0, 16, v136
	v_mul_f32_e32 v0, v90, v0
	v_and_b32_e32 v90, 0xffff0000, v136
	v_mul_f32_e32 v90, v91, v90
	v_cvt_pk_bf16_f32 v96, v0, v90
	v_mul_f32_e32 v90, 0xbfb8aa3b, v92
	v_exp_f32_e32 v90, v90
	v_mul_f32_e32 v91, 0xbfb8aa3b, v93
	v_exp_f32_e32 v91, v91
	v_mul_f32_e32 v86, 0xbfb8aa3b, v86
	v_exp_f32_e32 v86, v86
	v_mul_f32_e32 v87, 0xbfb8aa3b, v87
	v_exp_f32_e32 v87, v87
	v_add_f32_e32 v90, 1.0, v90
	v_rcp_f32_e32 v90, v90
	v_add_f32_e32 v91, 1.0, v91
	v_rcp_f32_e32 v91, v91
	v_add_f32_e32 v86, 1.0, v86
	v_rcp_f32_e32 v86, v86
	v_add_f32_e32 v87, 1.0, v87
	v_lshlrev_b32_e32 v0, 16, v137
	v_rcp_f32_e32 v87, v87
	v_mul_f32_e32 v0, v90, v0
	v_and_b32_e32 v90, 0xffff0000, v137
	v_mul_f32_e32 v90, v91, v90
	v_cvt_pk_bf16_f32 v97, v0, v90
	v_lshlrev_b32_e32 v0, 16, v130
	v_mul_f32_e32 v0, v86, v0
	v_and_b32_e32 v86, 0xffff0000, v130
	v_mul_f32_e32 v86, v87, v86
	v_mul_f32_e32 v87, 0xbfb8aa3b, v88
	v_exp_f32_e32 v87, v87
	v_mul_f32_e32 v88, 0xbfb8aa3b, v89
	v_exp_f32_e32 v88, v88
	v_mul_f32_e32 v82, 0xbfb8aa3b, v82
	v_exp_f32_e32 v82, v82
	v_mul_f32_e32 v83, 0xbfb8aa3b, v83
	v_add_f32_e32 v87, 1.0, v87
	v_exp_f32_e32 v83, v83
	v_rcp_f32_e32 v87, v87
	v_add_f32_e32 v88, 1.0, v88
	v_add_co_u32_e32 v90, vcc, s91, v164
	v_rcp_f32_e32 v88, v88
	s_nop 0
	v_addc_co_u32_e32 v91, vcc, 0, v165, vcc
	v_add_f32_e32 v82, 1.0, v82
	global_store_dwordx4 v[90:91], v[94:97], off
	v_cvt_pk_bf16_f32 v86, v0, v86
	v_lshlrev_b32_e32 v0, 16, v131
	v_rcp_f32_e32 v82, v82
	v_add_f32_e32 v83, 1.0, v83
	v_mul_f32_e32 v0, v87, v0
	v_and_b32_e32 v87, 0xffff0000, v131
	v_rcp_f32_e32 v83, v83
	v_mul_f32_e32 v87, v88, v87
	v_cvt_pk_bf16_f32 v87, v0, v87
	v_lshlrev_b32_e32 v0, 16, v132
	v_mul_f32_e32 v0, v82, v0
	v_and_b32_e32 v82, 0xffff0000, v132
	v_mul_f32_e32 v82, v83, v82
	v_cvt_pk_bf16_f32 v88, v0, v82
	v_mul_f32_e32 v82, 0xbfb8aa3b, v84
	v_exp_f32_e32 v82, v82
	v_mul_f32_e32 v83, 0xbfb8aa3b, v85
	v_exp_f32_e32 v83, v83
	v_mul_f32_e32 v78, 0xbfb8aa3b, v78
	v_exp_f32_e32 v78, v78
	v_mul_f32_e32 v79, 0xbfb8aa3b, v79
	v_exp_f32_e32 v79, v79
	v_add_f32_e32 v82, 1.0, v82
	v_rcp_f32_e32 v82, v82
	v_add_f32_e32 v83, 1.0, v83
	v_rcp_f32_e32 v83, v83
	v_add_f32_e32 v78, 1.0, v78
	v_rcp_f32_e32 v78, v78
	v_add_f32_e32 v79, 1.0, v79
	v_lshlrev_b32_e32 v0, 16, v133
	v_rcp_f32_e32 v79, v79
; __device__ __forceinline__ float fexp(float x) { return __builtin_amdgcn_exp2f(x * 1.4426950408889634f); }
; __device__ __forceinline__ float bflo_(unsigned w) { return __uint_as_float(w << 16); }
; __device__ __forceinline__ float bfhi_(unsigned w) { return __uint_as_float(w & 0xffff0000u); }
; __device__ __forceinline__ unsigned cvt_pk_bf16(float lo, float hi) { unsigned r; asm volatile("v_cvt_pk_bf16_f32 %0, %1, %2" : "=v"(r) : "v"(lo), "v"(hi)); return r; }
;     __device__ __forceinline__ void operator()(const f32x4 (&acc)[2][2][4][2], const Unit& u, int wr, int wc, int fr, int fq) const {
;     ...
;             for (int m = 0; m < 4; ++m)
; #pragma unroll
;                 for (int bj = 0; bj < 2; ++bj) yv[m][bj] = *(const u32x4*)(py + m * sy + bj * HALF * 2);
;             asm volatile("" ::: "memory");
; #pragma unroll
;             for (int m = 0; m < 4; ++m)
; #pragma unroll
;                 for (int bj = 0; bj < 2; ++bj) { const f32x4 v0 = acc[ai][bj][m][0], v1 = acc[ai][bj][m][1]; const u32x4 y = yv[m][bj];
;                     u32x4 w;
;                     w.x = cvt_pk_bf16(bflo_(y.x) * __builtin_amdgcn_rcpf(1.f + fexp(-v0[0])), bfhi_(y.x) * __builtin_amdgcn_rcpf(1.f + fexp(-v0[1])));
;                     w.y = cvt_pk_bf16(bflo_(y.y) * __builtin_amdgcn_rcpf(1.f + fexp(-v0[2])), bfhi_(y.y) * __builtin_amdgcn_rcpf(1.f + fexp(-v0[3])));
;                     w.z = cvt_pk_bf16(bflo_(y.z) * __builtin_amdgcn_rcpf(1.f + fexp(-v1[0])), bfhi_(y.z) * __builtin_amdgcn_rcpf(1.f + fexp(-v1[1])));
;                     w.w = cvt_pk_bf16(bflo_(y.w) * __builtin_amdgcn_rcpf(1.f + fexp(-v1[2])), bfhi_(y.w) * __builtin_amdgcn_rcpf(1.f + fexp(-v1[3])));
;                     *(u32x4*)(po + m * so + bj * HALF * 2) = w; }
;             py += 8 * sy; po += 8 * so;
	v_mul_f32_e32 v0, v82, v0
	v_and_b32_e32 v82, 0xffff0000, v133
	v_mul_f32_e32 v82, v83, v82
	v_cvt_pk_bf16_f32 v89, v0, v82
	v_lshlrev_b32_e32 v0, 16, v118
	v_mul_f32_e32 v0, v78, v0
	v_and_b32_e32 v78, 0xffff0000, v118
	v_mul_f32_e32 v78, v79, v78
	v_mul_f32_e32 v79, 0xbfb8aa3b, v80
	v_exp_f32_e32 v79, v79
	v_mul_f32_e32 v80, 0xbfb8aa3b, v81
	v_exp_f32_e32 v80, v80
	v_mul_f32_e32 v74, 0xbfb8aa3b, v74
	v_exp_f32_e32 v74, v74
	v_mul_f32_e32 v75, 0xbfb8aa3b, v75
	v_add_f32_e32 v79, 1.0, v79
	v_exp_f32_e32 v75, v75
	v_rcp_f32_e32 v79, v79
	v_add_f32_e32 v80, 1.0, v80
	v_rcp_f32_e32 v80, v80
	v_add_f32_e32 v74, 1.0, v74
	global_store_dwordx4 v[90:91], v[86:89], off offset:256
	v_cvt_pk_bf16_f32 v78, v0, v78
	v_lshlrev_b32_e32 v0, 16, v119
	v_rcp_f32_e32 v74, v74
	v_add_f32_e32 v75, 1.0, v75
	v_mul_f32_e32 v0, v79, v0
	v_and_b32_e32 v79, 0xffff0000, v119
	v_rcp_f32_e32 v75, v75
	v_mul_f32_e32 v79, v80, v79
	v_cvt_pk_bf16_f32 v79, v0, v79
	v_lshlrev_b32_e32 v0, 16, v120
	v_mul_f32_e32 v0, v74, v0
	v_and_b32_e32 v74, 0xffff0000, v120
	v_mul_f32_e32 v74, v75, v74
	v_cvt_pk_bf16_f32 v80, v0, v74
	v_mul_f32_e32 v74, 0xbfb8aa3b, v76
	v_exp_f32_e32 v74, v74
	v_mul_f32_e32 v75, 0xbfb8aa3b, v77
	v_exp_f32_e32 v75, v75
	v_mul_f32_e32 v70, 0xbfb8aa3b, v70
	v_exp_f32_e32 v70, v70
	v_mul_f32_e32 v71, 0xbfb8aa3b, v71
	v_exp_f32_e32 v71, v71
	v_add_f32_e32 v74, 1.0, v74
	v_rcp_f32_e32 v74, v74
	v_add_f32_e32 v75, 1.0, v75
	v_rcp_f32_e32 v75, v75
	v_add_f32_e32 v70, 1.0, v70
	v_rcp_f32_e32 v70, v70
	v_add_f32_e32 v71, 1.0, v71
	v_lshlrev_b32_e32 v0, 16, v121
	v_rcp_f32_e32 v71, v71
	v_mul_f32_e32 v0, v74, v0
	v_and_b32_e32 v74, 0xffff0000, v121
	v_mul_f32_e32 v74, v75, v74
	v_cvt_pk_bf16_f32 v81, v0, v74
	v_lshlrev_b32_e32 v0, 16, v106
	v_mul_f32_e32 v0, v70, v0
	v_and_b32_e32 v70, 0xffff0000, v106
	v_mul_f32_e32 v70, v71, v70
	v_mul_f32_e32 v71, 0xbfb8aa3b, v72
	v_exp_f32_e32 v71, v71
	v_mul_f32_e32 v72, 0xbfb8aa3b, v73
	v_exp_f32_e32 v72, v72
	v_mul_f32_e32 v66, 0xbfb8aa3b, v66
	v_exp_f32_e32 v66, v66
	v_mul_f32_e32 v67, 0xbfb8aa3b, v67
	v_add_f32_e32 v71, 1.0, v71
	v_exp_f32_e32 v67, v67
	v_rcp_f32_e32 v71, v71
	v_add_f32_e32 v72, 1.0, v72
	v_add_co_u32_e32 v74, vcc, s86, v164
	v_rcp_f32_e32 v72, v72
	s_nop 0
	v_addc_co_u32_e32 v75, vcc, 0, v165, vcc
	v_add_f32_e32 v66, 1.0, v66
	global_store_dwordx4 v[74:75], v[78:81], off
	v_cvt_pk_bf16_f32 v70, v0, v70
	v_lshlrev_b32_e32 v0, 16, v107
	v_rcp_f32_e32 v66, v66
	v_add_f32_e32 v67, 1.0, v67
	v_mul_f32_e32 v0, v71, v0
	v_and_b32_e32 v71, 0xffff0000, v107
	v_rcp_f32_e32 v67, v67
	v_mul_f32_e32 v71, v72, v71
	v_cvt_pk_bf16_f32 v71, v0, v71
	v_lshlrev_b32_e32 v0, 16, v108
	v_mul_f32_e32 v0, v66, v0
	v_and_b32_e32 v66, 0xffff0000, v108
	v_mul_f32_e32 v66, v67, v66
	v_cvt_pk_bf16_f32 v72, v0, v66
	v_mul_f32_e32 v66, 0xbfb8aa3b, v68
	v_exp_f32_e32 v66, v66
	v_mul_f32_e32 v67, 0xbfb8aa3b, v69
	v_exp_f32_e32 v67, v67
	v_lshlrev_b32_e32 v0, 16, v109
	v_add_f32_e32 v66, 1.0, v66
	v_rcp_f32_e32 v66, v66
	v_add_f32_e32 v67, 1.0, v67
	v_rcp_f32_e32 v67, v67
	s_mov_b64 s[2:3], 0x10000
	v_mul_f32_e32 v0, v66, v0
	v_and_b32_e32 v66, 0xffff0000, v109
	v_mul_f32_e32 v66, v67, v66
	v_cvt_pk_bf16_f32 v73, v0, v66
	v_lshl_add_u64 v[66:67], v[162:163], 0, s[2:3]
	global_store_dwordx4 v[74:75], v[70:73], off offset:256
	v_lshl_add_u64 v[94:95], v[164:165], 0, s[24:25]
	global_load_dwordx4 v[96:99], v[66:67], off
	global_load_dwordx4 v[90:93], v[66:67], off offset:256
	v_add_co_u32_e32 v68, vcc, s1, v66
	v_mul_f32_e32 v62, 0xbfb8aa3b, v62
	s_nop 0
	v_addc_co_u32_e32 v69, vcc, 0, v67, vcc
	global_load_dwordx4 v[86:89], v[68:69], off
	global_load_dwordx4 v[82:85], v[68:69], off offset:256
	v_exp_f32_e32 v62, v62
	v_mul_f32_e32 v63, 0xbfb8aa3b, v63
	v_exp_f32_e32 v63, v63
	v_mul_f32_e32 v58, 0xbfb8aa3b, v58
	v_add_f32_e32 v62, 1.0, v62
	v_rcp_f32_e32 v62, v62
	v_add_f32_e32 v63, 1.0, v63
	v_rcp_f32_e32 v63, v63
	v_exp_f32_e32 v58, v58
	v_mul_f32_e32 v59, 0xbfb8aa3b, v59
	v_add_co_u32_e32 v68, vcc, s4, v66
	v_exp_f32_e32 v59, v59
	s_nop 0
	v_addc_co_u32_e32 v69, vcc, 0, v67, vcc
	v_add_co_u32_e32 v66, vcc, s8, v66
	v_add_f32_e32 v58, 1.0, v58
	s_nop 0
	v_addc_co_u32_e32 v67, vcc, 0, v67, vcc
	global_load_dwordx4 v[78:81], v[68:69], off
	global_load_dwordx4 v[74:77], v[68:69], off offset:256
	global_load_dwordx4 v[70:73], v[66:67], off
	s_nop 0
	global_load_dwordx4 v[66:69], v[66:67], off offset:256
	v_rcp_f32_e32 v58, v58
	v_add_f32_e32 v59, 1.0, v59
	v_rcp_f32_e32 v59, v59
	v_mul_f32_e32 v54, 0xbfb8aa3b, v54
	v_exp_f32_e32 v54, v54
	v_mul_f32_e32 v55, 0xbfb8aa3b, v55
	v_exp_f32_e32 v55, v55
	v_mul_f32_e32 v50, 0xbfb8aa3b, v50
	v_add_f32_e32 v54, 1.0, v54
	v_rcp_f32_e32 v54, v54
	v_add_f32_e32 v55, 1.0, v55
	v_rcp_f32_e32 v55, v55
	v_exp_f32_e32 v50, v50
	v_mul_f32_e32 v51, 0xbfb8aa3b, v51
	v_exp_f32_e32 v51, v51
	v_mul_f32_e32 v46, 0xbfb8aa3b, v46
	v_add_f32_e32 v50, 1.0, v50
	v_rcp_f32_e32 v50, v50
	v_add_f32_e32 v51, 1.0, v51
	v_rcp_f32_e32 v51, v51
	v_exp_f32_e32 v46, v46
	v_mul_f32_e32 v47, 0xbfb8aa3b, v47
	v_exp_f32_e32 v47, v47
	v_mul_f32_e32 v42, 0xbfb8aa3b, v42
	v_add_f32_e32 v46, 1.0, v46
	v_rcp_f32_e32 v46, v46
	v_add_f32_e32 v47, 1.0, v47
	v_rcp_f32_e32 v47, v47
	v_exp_f32_e32 v42, v42
	v_mul_f32_e32 v43, 0xbfb8aa3b, v43
	v_exp_f32_e32 v43, v43
	v_mul_f32_e32 v38, 0xbfb8aa3b, v38
	v_add_f32_e32 v42, 1.0, v42
	v_rcp_f32_e32 v42, v42
	v_add_f32_e32 v43, 1.0, v43
	v_rcp_f32_e32 v43, v43
	v_exp_f32_e32 v38, v38
	v_mul_f32_e32 v39, 0xbfb8aa3b, v39
	v_exp_f32_e32 v39, v39
	v_mul_f32_e32 v34, 0xbfb8aa3b, v34
	v_add_f32_e32 v38, 1.0, v38
	v_rcp_f32_e32 v38, v38
	v_add_f32_e32 v39, 1.0, v39
	v_rcp_f32_e32 v39, v39
	v_exp_f32_e32 v34, v34
	v_mul_f32_e32 v35, 0xbfb8aa3b, v35
	v_exp_f32_e32 v35, v35
	v_mul_f32_e32 v30, 0xbfb8aa3b, v30
	v_add_f32_e32 v34, 1.0, v34
	s_waitcnt vmcnt(0) lgkmcnt(0)
; __device__ __forceinline__ float fexp(float x) { return __builtin_amdgcn_exp2f(x * 1.4426950408889634f); }
; __device__ __forceinline__ float bflo_(unsigned w) { return __uint_as_float(w << 16); }
; __device__ __forceinline__ float bfhi_(unsigned w) { return __uint_as_float(w & 0xffff0000u); }
; __device__ __forceinline__ unsigned cvt_pk_bf16(float lo, float hi) { unsigned r; asm volatile("v_cvt_pk_bf16_f32 %0, %1, %2" : "=v"(r) : "v"(lo), "v"(hi)); return r; }
;     __device__ __forceinline__ void operator()(const f32x4 (&acc)[2][2][4][2], const Unit& u, int wr, int wc, int fr, int fq) const {
;     ...
;             for (int m = 0; m < 4; ++m)
; #pragma unroll
;                 for (int bj = 0; bj < 2; ++bj) yv[m][bj] = *(const u32x4*)(py + m * sy + bj * HALF * 2);
;             asm volatile("" ::: "memory");
; #pragma unroll
;             for (int m = 0; m < 4; ++m)
; #pragma unroll
;                 for (int bj = 0; bj < 2; ++bj) { const f32x4 v0 = acc[ai][bj][m][0], v1 = acc[ai][bj][m][1]; const u32x4 y = yv[m][bj];
;                     u32x4 w;
;                     w.x = cvt_pk_bf16(bflo_(y.x) * __builtin_amdgcn_rcpf(1.f + fexp(-v0[0])), bfhi_(y.x) * __builtin_amdgcn_rcpf(1.f + fexp(-v0[1])));
;                     w.y = cvt_pk_bf16(bflo_(y.y) * __builtin_amdgcn_rcpf(1.f + fexp(-v0[2])), bfhi_(y.y) * __builtin_amdgcn_rcpf(1.f + fexp(-v0[3])));
;                     w.z = cvt_pk_bf16(bflo_(y.z) * __builtin_amdgcn_rcpf(1.f + fexp(-v1[0])), bfhi_(y.z) * __builtin_amdgcn_rcpf(1.f + fexp(-v1[1])));
;                     w.w = cvt_pk_bf16(bflo_(y.w) * __builtin_amdgcn_rcpf(1.f + fexp(-v1[2])), bfhi_(y.w) * __builtin_amdgcn_rcpf(1.f + fexp(-v1[3])));
;                     *(u32x4*)(po + m * so + bj * HALF * 2) = w; }
;             py += 8 * sy; po += 8 * so;
	v_lshlrev_b32_e32 v0, 16, v96
	v_mul_f32_e32 v0, v62, v0
	v_and_b32_e32 v62, 0xffff0000, v96
	v_mul_f32_e32 v62, v63, v62
	v_mul_f32_e32 v63, 0xbfb8aa3b, v64
	v_exp_f32_e32 v63, v63
	v_mul_f32_e32 v64, 0xbfb8aa3b, v65
	v_exp_f32_e32 v64, v64
	v_cvt_pk_bf16_f32 v62, v0, v62
	v_add_f32_e32 v63, 1.0, v63
	v_rcp_f32_e32 v63, v63
	v_add_f32_e32 v64, 1.0, v64
	v_rcp_f32_e32 v64, v64
	v_lshlrev_b32_e32 v0, 16, v97
	v_mul_f32_e32 v0, v63, v0
	v_and_b32_e32 v63, 0xffff0000, v97
	v_mul_f32_e32 v63, v64, v63
	v_cvt_pk_bf16_f32 v63, v0, v63
	v_lshlrev_b32_e32 v0, 16, v98
	v_mul_f32_e32 v0, v58, v0
	v_and_b32_e32 v58, 0xffff0000, v98
	v_mul_f32_e32 v58, v59, v58
	v_cvt_pk_bf16_f32 v64, v0, v58
	v_mul_f32_e32 v58, 0xbfb8aa3b, v60
	v_exp_f32_e32 v58, v58
	v_mul_f32_e32 v59, 0xbfb8aa3b, v61
	v_exp_f32_e32 v59, v59
	v_lshlrev_b32_e32 v0, 16, v99
	v_add_f32_e32 v58, 1.0, v58
	v_rcp_f32_e32 v58, v58
	v_add_f32_e32 v59, 1.0, v59
	v_rcp_f32_e32 v59, v59
	v_rcp_f32_e32 v34, v34
	v_mul_f32_e32 v0, v58, v0
	v_and_b32_e32 v58, 0xffff0000, v99
	v_mul_f32_e32 v58, v59, v58
	v_cvt_pk_bf16_f32 v65, v0, v58
	v_lshlrev_b32_e32 v0, 16, v90
	v_mul_f32_e32 v0, v54, v0
	v_and_b32_e32 v54, 0xffff0000, v90
	v_mul_f32_e32 v54, v55, v54
	v_mul_f32_e32 v55, 0xbfb8aa3b, v56
	v_exp_f32_e32 v55, v55
	v_mul_f32_e32 v56, 0xbfb8aa3b, v57
	v_exp_f32_e32 v56, v56
	global_store_dwordx4 v[94:95], v[62:65], off
	v_add_f32_e32 v55, 1.0, v55
	v_rcp_f32_e32 v55, v55
	v_add_f32_e32 v56, 1.0, v56
	v_rcp_f32_e32 v56, v56
	v_cvt_pk_bf16_f32 v54, v0, v54
	v_lshlrev_b32_e32 v0, 16, v91
	v_mul_f32_e32 v0, v55, v0
	v_and_b32_e32 v55, 0xffff0000, v91
	v_mul_f32_e32 v55, v56, v55
	v_cvt_pk_bf16_f32 v55, v0, v55
	v_lshlrev_b32_e32 v0, 16, v92
	v_mul_f32_e32 v0, v50, v0
	v_and_b32_e32 v50, 0xffff0000, v92
	v_mul_f32_e32 v50, v51, v50
	v_cvt_pk_bf16_f32 v56, v0, v50
	v_mul_f32_e32 v50, 0xbfb8aa3b, v52
	v_exp_f32_e32 v50, v50
	v_mul_f32_e32 v51, 0xbfb8aa3b, v53
	v_exp_f32_e32 v51, v51
	v_lshlrev_b32_e32 v0, 16, v93
	v_add_f32_e32 v50, 1.0, v50
	v_rcp_f32_e32 v50, v50
	v_add_f32_e32 v51, 1.0, v51
	v_rcp_f32_e32 v51, v51
	v_add_f32_e32 v35, 1.0, v35
	v_mul_f32_e32 v0, v50, v0
	v_and_b32_e32 v50, 0xffff0000, v93
	v_mul_f32_e32 v50, v51, v50
	v_cvt_pk_bf16_f32 v57, v0, v50
	v_lshlrev_b32_e32 v0, 16, v86
	v_mul_f32_e32 v0, v46, v0
	v_and_b32_e32 v46, 0xffff0000, v86
	v_mul_f32_e32 v46, v47, v46
	v_mul_f32_e32 v47, 0xbfb8aa3b, v48
	v_exp_f32_e32 v47, v47
	v_mul_f32_e32 v48, 0xbfb8aa3b, v49
	v_exp_f32_e32 v48, v48
	global_store_dwordx4 v[94:95], v[54:57], off offset:256
	v_add_f32_e32 v47, 1.0, v47
	v_rcp_f32_e32 v47, v47
	v_add_f32_e32 v48, 1.0, v48
	v_rcp_f32_e32 v48, v48
	v_cvt_pk_bf16_f32 v46, v0, v46
	v_lshlrev_b32_e32 v0, 16, v87
	v_mul_f32_e32 v0, v47, v0
	v_and_b32_e32 v47, 0xffff0000, v87
	v_mul_f32_e32 v47, v48, v47
	v_cvt_pk_bf16_f32 v47, v0, v47
	v_lshlrev_b32_e32 v0, 16, v88
	v_mul_f32_e32 v0, v42, v0
	v_and_b32_e32 v42, 0xffff0000, v88
	v_mul_f32_e32 v42, v43, v42
	v_cvt_pk_bf16_f32 v48, v0, v42
	v_mul_f32_e32 v42, 0xbfb8aa3b, v44
	v_exp_f32_e32 v42, v42
	v_mul_f32_e32 v43, 0xbfb8aa3b, v45
	v_exp_f32_e32 v43, v43
	v_lshlrev_b32_e32 v0, 16, v89
	v_add_f32_e32 v42, 1.0, v42
	v_rcp_f32_e32 v42, v42
	v_add_f32_e32 v43, 1.0, v43
	v_rcp_f32_e32 v43, v43
	v_rcp_f32_e32 v35, v35
	v_mul_f32_e32 v0, v42, v0
	v_and_b32_e32 v42, 0xffff0000, v89
	v_mul_f32_e32 v42, v43, v42
	v_cvt_pk_bf16_f32 v49, v0, v42
	v_lshlrev_b32_e32 v0, 16, v82
	v_mul_f32_e32 v0, v38, v0
	v_and_b32_e32 v38, 0xffff0000, v82
	v_mul_f32_e32 v38, v39, v38
	v_mul_f32_e32 v39, 0xbfb8aa3b, v40
	v_exp_f32_e32 v39, v39
	v_mul_f32_e32 v40, 0xbfb8aa3b, v41
	v_exp_f32_e32 v40, v40
	v_add_co_u32_e32 v42, vcc, s87, v94
	v_add_f32_e32 v39, 1.0, v39
	v_rcp_f32_e32 v39, v39
	v_add_f32_e32 v40, 1.0, v40
	v_rcp_f32_e32 v40, v40
	v_addc_co_u32_e32 v43, vcc, 0, v95, vcc
	global_store_dwordx4 v[42:43], v[46:49], off
	v_cvt_pk_bf16_f32 v38, v0, v38
	v_lshlrev_b32_e32 v0, 16, v83
	v_mul_f32_e32 v0, v39, v0
	v_and_b32_e32 v39, 0xffff0000, v83
	v_mul_f32_e32 v39, v40, v39
	v_cvt_pk_bf16_f32 v39, v0, v39
	v_lshlrev_b32_e32 v0, 16, v84
	v_mul_f32_e32 v0, v34, v0
	v_and_b32_e32 v34, 0xffff0000, v84
	v_mul_f32_e32 v34, v35, v34
	v_cvt_pk_bf16_f32 v40, v0, v34
	v_mul_f32_e32 v34, 0xbfb8aa3b, v36
	v_exp_f32_e32 v34, v34
	v_mul_f32_e32 v35, 0xbfb8aa3b, v37
	v_exp_f32_e32 v35, v35
	v_exp_f32_e32 v30, v30
	v_mul_f32_e32 v31, 0xbfb8aa3b, v31
	v_exp_f32_e32 v31, v31
	v_add_f32_e32 v34, 1.0, v34
	v_rcp_f32_e32 v34, v34
	v_add_f32_e32 v35, 1.0, v35
	v_rcp_f32_e32 v35, v35
	v_add_f32_e32 v30, 1.0, v30
	v_rcp_f32_e32 v30, v30
	v_add_f32_e32 v31, 1.0, v31
	v_lshlrev_b32_e32 v0, 16, v85
	v_rcp_f32_e32 v31, v31
	v_mul_f32_e32 v0, v34, v0
	v_and_b32_e32 v34, 0xffff0000, v85
	v_mul_f32_e32 v34, v35, v34
	v_cvt_pk_bf16_f32 v41, v0, v34
	v_lshlrev_b32_e32 v0, 16, v78
	v_mul_f32_e32 v0, v30, v0
	v_and_b32_e32 v30, 0xffff0000, v78
	v_mul_f32_e32 v30, v31, v30
	v_mul_f32_e32 v31, 0xbfb8aa3b, v32
	v_exp_f32_e32 v31, v31
	v_mul_f32_e32 v32, 0xbfb8aa3b, v33
	v_exp_f32_e32 v32, v32
	v_mul_f32_e32 v26, 0xbfb8aa3b, v26
	v_exp_f32_e32 v26, v26
	v_mul_f32_e32 v27, 0xbfb8aa3b, v27
	v_add_f32_e32 v31, 1.0, v31
	v_exp_f32_e32 v27, v27
	v_rcp_f32_e32 v31, v31
	v_add_f32_e32 v32, 1.0, v32
	v_rcp_f32_e32 v32, v32
	v_add_f32_e32 v26, 1.0, v26
	global_store_dwordx4 v[42:43], v[38:41], off offset:256
	v_cvt_pk_bf16_f32 v30, v0, v30
	v_lshlrev_b32_e32 v0, 16, v79
	v_rcp_f32_e32 v26, v26
	v_add_f32_e32 v27, 1.0, v27
	v_mul_f32_e32 v0, v31, v0
	v_and_b32_e32 v31, 0xffff0000, v79
	v_rcp_f32_e32 v27, v27
	v_mul_f32_e32 v31, v32, v31
	v_cvt_pk_bf16_f32 v31, v0, v31
	v_lshlrev_b32_e32 v0, 16, v80
; __device__ __forceinline__ float fexp(float x) { return __builtin_amdgcn_exp2f(x * 1.4426950408889634f); }
; __device__ __forceinline__ float bflo_(unsigned w) { return __uint_as_float(w << 16); }
; __device__ __forceinline__ float bfhi_(unsigned w) { return __uint_as_float(w & 0xffff0000u); }
; __device__ __forceinline__ unsigned cvt_pk_bf16(float lo, float hi) { unsigned r; asm volatile("v_cvt_pk_bf16_f32 %0, %1, %2" : "=v"(r) : "v"(lo), "v"(hi)); return r; }
; __device__ __forceinline__ void block_fence() { __builtin_amdgcn_fence(__ATOMIC_RELEASE, "workgroup"); __syncthreads(); __builtin_amdgcn_fence(__ATOMIC_ACQUIRE, "workgroup"); }
;     __device__ __forceinline__ void operator()(const f32x4 (&acc)[2][2][4][2], const Unit& u, int wr, int wc, int fr, int fq) const {
;     ...
;             for (int m = 0; m < 4; ++m)
; #pragma unroll
;                 for (int bj = 0; bj < 2; ++bj) { const f32x4 v0 = acc[ai][bj][m][0], v1 = acc[ai][bj][m][1]; const u32x4 y = yv[m][bj];
;                     u32x4 w;
;                     w.x = cvt_pk_bf16(bflo_(y.x) * __builtin_amdgcn_rcpf(1.f + fexp(-v0[0])), bfhi_(y.x) * __builtin_amdgcn_rcpf(1.f + fexp(-v0[1])));
;                     w.y = cvt_pk_bf16(bflo_(y.y) * __builtin_amdgcn_rcpf(1.f + fexp(-v0[2])), bfhi_(y.y) * __builtin_amdgcn_rcpf(1.f + fexp(-v0[3])));
;                     w.z = cvt_pk_bf16(bflo_(y.z) * __builtin_amdgcn_rcpf(1.f + fexp(-v1[0])), bfhi_(y.z) * __builtin_amdgcn_rcpf(1.f + fexp(-v1[1])));
;                     w.w = cvt_pk_bf16(bflo_(y.w) * __builtin_amdgcn_rcpf(1.f + fexp(-v1[2])), bfhi_(y.w) * __builtin_amdgcn_rcpf(1.f + fexp(-v1[3])));
;                     *(u32x4*)(po + m * so + bj * HALF * 2) = w; }
;             py += 8 * sy; po += 8 * so;
; __global__ void __launch_bounds__(512, 2) fwd_megakernel(Args a) {
;     ...
;         block_fence();
	v_mul_f32_e32 v0, v26, v0
	v_and_b32_e32 v26, 0xffff0000, v80
	v_mul_f32_e32 v26, v27, v26
	v_cvt_pk_bf16_f32 v32, v0, v26
	v_mul_f32_e32 v26, 0xbfb8aa3b, v28
	v_exp_f32_e32 v26, v26
	v_mul_f32_e32 v27, 0xbfb8aa3b, v29
	v_exp_f32_e32 v27, v27
	v_mul_f32_e32 v22, 0xbfb8aa3b, v22
	v_exp_f32_e32 v22, v22
	v_mul_f32_e32 v23, 0xbfb8aa3b, v23
	v_exp_f32_e32 v23, v23
	v_add_f32_e32 v26, 1.0, v26
	v_rcp_f32_e32 v26, v26
	v_add_f32_e32 v27, 1.0, v27
	v_rcp_f32_e32 v27, v27
	v_add_f32_e32 v22, 1.0, v22
	v_rcp_f32_e32 v22, v22
	v_add_f32_e32 v23, 1.0, v23
	v_lshlrev_b32_e32 v0, 16, v81
	v_rcp_f32_e32 v23, v23
	v_mul_f32_e32 v0, v26, v0
	v_and_b32_e32 v26, 0xffff0000, v81
	v_mul_f32_e32 v26, v27, v26
	v_cvt_pk_bf16_f32 v33, v0, v26
	v_lshlrev_b32_e32 v0, 16, v74
	v_mul_f32_e32 v0, v22, v0
	v_and_b32_e32 v22, 0xffff0000, v74
	v_mul_f32_e32 v22, v23, v22
	v_mul_f32_e32 v23, 0xbfb8aa3b, v24
	v_exp_f32_e32 v23, v23
	v_mul_f32_e32 v24, 0xbfb8aa3b, v25
	v_exp_f32_e32 v24, v24
	v_mul_f32_e32 v18, 0xbfb8aa3b, v18
	v_exp_f32_e32 v18, v18
	v_mul_f32_e32 v19, 0xbfb8aa3b, v19
	v_add_f32_e32 v23, 1.0, v23
	v_exp_f32_e32 v19, v19
	v_rcp_f32_e32 v23, v23
	v_add_f32_e32 v24, 1.0, v24
	v_add_co_u32_e32 v26, vcc, s91, v94
	v_rcp_f32_e32 v24, v24
	s_nop 0
	v_addc_co_u32_e32 v27, vcc, 0, v95, vcc
	v_add_f32_e32 v18, 1.0, v18
	global_store_dwordx4 v[26:27], v[30:33], off
	v_cvt_pk_bf16_f32 v22, v0, v22
	v_lshlrev_b32_e32 v0, 16, v75
	v_rcp_f32_e32 v18, v18
	v_add_f32_e32 v19, 1.0, v19
	v_mul_f32_e32 v0, v23, v0
	v_and_b32_e32 v23, 0xffff0000, v75
	v_rcp_f32_e32 v19, v19
	v_mul_f32_e32 v23, v24, v23
	v_cvt_pk_bf16_f32 v23, v0, v23
	v_lshlrev_b32_e32 v0, 16, v76
	v_mul_f32_e32 v0, v18, v0
	v_and_b32_e32 v18, 0xffff0000, v76
	v_mul_f32_e32 v18, v19, v18
	v_cvt_pk_bf16_f32 v24, v0, v18
	v_mul_f32_e32 v18, 0xbfb8aa3b, v20
	v_exp_f32_e32 v18, v18
	v_mul_f32_e32 v19, 0xbfb8aa3b, v21
	v_exp_f32_e32 v19, v19
	v_mul_f32_e32 v14, 0xbfb8aa3b, v14
	v_exp_f32_e32 v14, v14
	v_mul_f32_e32 v15, 0xbfb8aa3b, v15
	v_exp_f32_e32 v15, v15
	v_add_f32_e32 v18, 1.0, v18
	v_rcp_f32_e32 v18, v18
	v_add_f32_e32 v19, 1.0, v19
	v_rcp_f32_e32 v19, v19
	v_add_f32_e32 v14, 1.0, v14
	v_rcp_f32_e32 v14, v14
	v_add_f32_e32 v15, 1.0, v15
	v_lshlrev_b32_e32 v0, 16, v77
	v_rcp_f32_e32 v15, v15
	v_mul_f32_e32 v0, v18, v0
	v_and_b32_e32 v18, 0xffff0000, v77
	v_mul_f32_e32 v18, v19, v18
	v_cvt_pk_bf16_f32 v25, v0, v18
	v_lshlrev_b32_e32 v0, 16, v70
	v_mul_f32_e32 v0, v14, v0
	v_and_b32_e32 v14, 0xffff0000, v70
	v_mul_f32_e32 v14, v15, v14
	v_mul_f32_e32 v15, 0xbfb8aa3b, v16
	v_exp_f32_e32 v15, v15
	v_mul_f32_e32 v16, 0xbfb8aa3b, v17
	v_exp_f32_e32 v16, v16
	v_mul_f32_e32 v10, 0xbfb8aa3b, v10
	v_exp_f32_e32 v10, v10
	v_mul_f32_e32 v11, 0xbfb8aa3b, v11
	v_add_f32_e32 v15, 1.0, v15
	v_exp_f32_e32 v11, v11
	v_rcp_f32_e32 v15, v15
	v_add_f32_e32 v16, 1.0, v16
	v_rcp_f32_e32 v16, v16
	v_add_f32_e32 v10, 1.0, v10
	global_store_dwordx4 v[26:27], v[22:25], off offset:256
	v_cvt_pk_bf16_f32 v14, v0, v14
	v_lshlrev_b32_e32 v0, 16, v71
	v_rcp_f32_e32 v10, v10
	v_add_f32_e32 v11, 1.0, v11
	v_mul_f32_e32 v0, v15, v0
	v_and_b32_e32 v15, 0xffff0000, v71
	v_rcp_f32_e32 v11, v11
	v_mul_f32_e32 v15, v16, v15
	v_cvt_pk_bf16_f32 v15, v0, v15
	v_lshlrev_b32_e32 v0, 16, v72
	v_mul_f32_e32 v0, v10, v0
	v_and_b32_e32 v10, 0xffff0000, v72
	v_mul_f32_e32 v10, v11, v10
	v_cvt_pk_bf16_f32 v16, v0, v10
	v_mul_f32_e32 v10, 0xbfb8aa3b, v12
	v_exp_f32_e32 v10, v10
	v_mul_f32_e32 v11, 0xbfb8aa3b, v13
	v_exp_f32_e32 v11, v11
	v_mul_f32_e32 v6, 0xbfb8aa3b, v6
	v_exp_f32_e32 v6, v6
	v_mul_f32_e32 v7, 0xbfb8aa3b, v7
	v_exp_f32_e32 v7, v7
	v_add_f32_e32 v10, 1.0, v10
	v_rcp_f32_e32 v10, v10
	v_add_f32_e32 v11, 1.0, v11
	v_rcp_f32_e32 v11, v11
	v_add_f32_e32 v6, 1.0, v6
	v_rcp_f32_e32 v6, v6
	v_add_f32_e32 v7, 1.0, v7
	v_lshlrev_b32_e32 v0, 16, v73
	v_rcp_f32_e32 v7, v7
	v_mul_f32_e32 v0, v10, v0
	v_and_b32_e32 v10, 0xffff0000, v73
	v_mul_f32_e32 v10, v11, v10
	v_cvt_pk_bf16_f32 v17, v0, v10
	v_lshlrev_b32_e32 v0, 16, v66
	v_mul_f32_e32 v0, v6, v0
	v_and_b32_e32 v6, 0xffff0000, v66
	v_mul_f32_e32 v6, v7, v6
	v_mul_f32_e32 v7, 0xbfb8aa3b, v8
	v_exp_f32_e32 v7, v7
	v_mul_f32_e32 v8, 0xbfb8aa3b, v9
	v_exp_f32_e32 v8, v8
	v_mul_f32_e32 v2, 0xbfb8aa3b, v2
	v_exp_f32_e32 v2, v2
	v_mul_f32_e32 v3, 0xbfb8aa3b, v3
	v_add_f32_e32 v7, 1.0, v7
	v_exp_f32_e32 v3, v3
	v_rcp_f32_e32 v7, v7
	v_add_f32_e32 v8, 1.0, v8
	v_add_co_u32_e32 v10, vcc, s86, v94
	v_rcp_f32_e32 v8, v8
	s_nop 0
	v_addc_co_u32_e32 v11, vcc, 0, v95, vcc
	v_add_f32_e32 v2, 1.0, v2
	global_store_dwordx4 v[10:11], v[14:17], off
	v_cvt_pk_bf16_f32 v6, v0, v6
	v_lshlrev_b32_e32 v0, 16, v67
	v_rcp_f32_e32 v2, v2
	v_add_f32_e32 v3, 1.0, v3
	v_mul_f32_e32 v0, v7, v0
	v_and_b32_e32 v7, 0xffff0000, v67
	v_rcp_f32_e32 v3, v3
	v_mul_f32_e32 v7, v8, v7
	v_cvt_pk_bf16_f32 v7, v0, v7
	v_lshlrev_b32_e32 v0, 16, v68
	v_mul_f32_e32 v0, v2, v0
	v_and_b32_e32 v2, 0xffff0000, v68
	v_mul_f32_e32 v2, v3, v2
	v_cvt_pk_bf16_f32 v8, v0, v2
	v_mul_f32_e32 v2, 0xbfb8aa3b, v4
	v_exp_f32_e32 v2, v2
	v_mul_f32_e32 v3, 0xbfb8aa3b, v5
	v_exp_f32_e32 v3, v3
	v_lshlrev_b32_e32 v0, 16, v69
	v_add_f32_e32 v2, 1.0, v2
	v_rcp_f32_e32 v2, v2
	v_add_f32_e32 v3, 1.0, v3
	v_rcp_f32_e32 v3, v3
	v_readlane_b32 s2, v249, 0
	v_mul_f32_e32 v0, v2, v0
	v_and_b32_e32 v2, 0xffff0000, v69
	v_mul_f32_e32 v2, v3, v2
	v_cvt_pk_bf16_f32 v9, v0, v2
	global_store_dwordx4 v[10:11], v[6:9], off offset:256
	v_readlane_b32 s3, v249, 1
	v_mov_b32_e32 v16, v189
	s_waitcnt vmcnt(0)
	s_barrier
; #define PG8_STAGE(bufoff, gbase, voff) do { _Pragma("unroll") for (int _i = 0; _i < 2; ++_i) \
;         __builtin_amdgcn_global_load_lds((const unsigned*)((const char*)(gbase) + (voff)[_i]), (LAS unsigned*)(lds + (bufoff) + ldsw + _i * 8192), 16, 0, 0); } while (0)
; #define PG8_WAIT_V(n) asm volatile("s_waitcnt vmcnt(" #n ")" ::: "memory")
; #define PG8_BAR __builtin_amdgcn_s_barrier()
; template <class Epi, class Sched>
; __device__ __forceinline__ void gemm_phase(LAS unsigned char* lds, const Gemm g, const Sched& S, const Epi& E) {
;     ...
;     unsigned voffA[2], voffB[2];
; #pragma unroll
;     for (int i = 0; i < 2; ++i) { int R, C; stage_rc(tid * 16 + i * 8192, R, C); const int Rb = Epi::PERM ? ((R & ~31) + perm32(R & 31)) : R;
;         voffA[i] = (unsigned)(R * K + C) * 2u; voffB[i] = (unsigned)(Rb * K + C) * 2u; }
;     const size_t kstep = (size_t)(BK * 2);
;     const size_t hstep = (size_t)HALF * K * 2;
;     const size_t tstep = 2 * hstep;
;     const unsigned ldsw = (unsigned)wid * 1024u;
;     const int aoff = lds_byte(wr * 64 + fr, fq * 8), boff = lds_byte(wc * 32 + fr, fq * 8);
;     ...
;     Unit cur, nxt; int ui = 0;
;     if (!S.next(0, cur)) return;
;     f32x4 acc[2][2][4][2];
; #pragma unroll
;     for (int a = 0; a < 2; ++a)
; #pragma unroll
;         for (int b = 0; b < 2; ++b)
; #pragma unroll
;             for (int m = 0; m < 4; ++m)
; #pragma unroll
;                 for (int n = 0; n < 2; ++n) acc[a][b][m][n] = (f32x4){0.f, 0.f, 0.f, 0.f};
;     bf16x8 At[4][2], B0[2][2], B1[2][2];
;     const char* cA = (const char*)g.A + (size_t)cur.pm * tstep; const char* cB = (const char*)g.Bt + (size_t)cur.pn * tstep;
;     S.a_ready(cur);
;     PG8_STAGE(PG8_SB(0, 0), cB, voffB); PG8_STAGE(PG8_SB(0, 1), cB + hstep, voffB); PG8_STAGE(PG8_SA(0, 0), cA, voffA); PG8_STAGE(PG8_SA(0, 1), cA + hstep, voffA);
;     if (wr == 1) PG8_BAR;
;     PG8_WAIT_V(2); PG8_BAR;
;     PG8_STAGE(PG8_SB(1, 0), cB + kstep, voffB); PG8_STAGE(PG8_SA(1, 0), cA + kstep, voffA); PG8_STAGE(PG8_SB(1, 1), cB + hstep + kstep, voffB);
;     PG8_WAIT_V(6); PG8_BAR;
	s_waitcnt lgkmcnt(0)
	s_barrier
	s_load_dwordx2 s[46:47], s[2:3], 0xf8
	s_movk_i32 s42, 0x400
	v_lshlrev_b32_e32 v0, 4, v16
	v_add_u32_e32 v2, 0x2000, v0
	v_ashrrev_i32_e32 v3, 31, v2
	v_lshrrev_b32_e32 v3, 22, v3
	v_add_u32_e32 v3, v2, v3
	v_ashrrev_i32_e32 v3, 10, v3
	v_mul_i32_i24_e32 v4, 0x400, v3
	v_sub_u32_e32 v2, v2, v4
	s_waitcnt lgkmcnt(0)
	s_add_u32 s1, s46, s88
	v_lshrrev_b32_e32 v4, 4, v2
	s_addc_u32 s9, s47, s89
	v_bitop3_b32 v2, v4, v2, 32 bitop3:0x6c
	s_add_u32 s2, s1, 0xe140000
	v_ashrrev_i32_e32 v4, 31, v2
	s_addc_u32 s3, s9, 0
	s_lshl_b64 s[4:5], s[18:19], 21
	v_lshrrev_b32_e32 v4, 26, v4
	s_add_u32 s4, s46, s4
	v_add_u32_e32 v4, v2, v4
	v_lshlrev_b32_e32 v6, 3, v3
	s_addc_u32 s5, s47, s5
	v_ashrrev_i32_e32 v5, 6, v4
	v_and_b32_e32 v6, -16, v6
	v_lshlrev_b32_e32 v3, 5, v3
	s_add_u32 s10, s4, 0xc00000
	v_add_u32_e32 v6, v5, v6
	v_and_b32_e32 v10, 32, v3
	v_and_b32_e32 v3, 0xc0, v4
	s_addc_u32 s11, s5, 0
	v_and_b32_e32 v5, 3, v5
	s_mov_b32 s5, 0x7fffffe0
	v_lshrrev_b32_e32 v7, 2, v6
	v_lshlrev_b32_e32 v8, 1, v6
	v_sub_u32_e32 v2, v2, v3
	v_and_or_b32 v5, v6, s5, v5
	v_and_b32_e32 v7, 4, v7
	v_and_b32_e32 v8, 24, v8
	v_ashrrev_i16_sdwa v2, v227, sext(v2) dst_sel:DWORD dst_unused:UNUSED_PAD src0_sel:DWORD src1_sel:BYTE_0
	v_or3_b32 v5, v5, v7, v8
	v_bfe_i32 v11, v2, 0, 16
	v_add_u32_e32 v2, v10, v11
	v_mul_lo_u32 v5, v5, s42
	v_mul_lo_u32 v12, v6, s42
	v_add_lshl_u32 v142, v5, v2, 1
	v_add_lshl_u32 v144, v2, v12, 1
	v_bfe_i32 v2, v16, 27, 1
	v_lshrrev_b32_e32 v2, 22, v2
	v_add_u32_e32 v2, v0, v2
	v_and_b32_e32 v2, 0xfffffc00, v2
	v_sub_u32_e32 v0, v0, v2
	v_lshrrev_b32_e32 v2, 4, v0
	v_ashrrev_i32_e32 v4, 31, v16
	v_bitop3_b32 v0, v2, v0, 32 bitop3:0x6c
	v_lshrrev_b32_e32 v4, 26, v4
	v_ashrrev_i32_e32 v2, 31, v0
	v_add_u32_e32 v4, v16, v4
	v_lshrrev_b32_e32 v2, 26, v2
	v_ashrrev_i32_e32 v4, 6, v4
	v_add_u32_e32 v2, v0, v2
	v_lshlrev_b32_e32 v5, 3, v4
	v_ashrrev_i32_e32 v3, 6, v2
	v_and_b32_e32 v5, -16, v5
	v_add_u32_e32 v5, v3, v5
	v_and_b32_e32 v2, 0xc0, v2
	v_readfirstlane_b32 s8, v16
	v_and_b32_e32 v3, 3, v3
	v_lshrrev_b32_e32 v6, 2, v5
	v_lshlrev_b32_e32 v7, 1, v5
	v_sub_u32_e32 v0, v0, v2
	s_ashr_i32 s36, s8, 6
	v_and_or_b32 v3, v5, s5, v3
	v_and_b32_e32 v6, 4, v6
	v_and_b32_e32 v7, 24, v7
	v_lshlrev_b32_e32 v4, 5, v4
	v_ashrrev_i16_sdwa v0, v227, sext(v0) dst_sel:DWORD dst_unused:UNUSED_PAD src0_sel:DWORD src1_sel:BYTE_0
	s_lshl_b32 s4, s36, 10
	v_or3_b32 v3, v3, v6, v7
	v_and_b32_e32 v13, 32, v4
	v_bfe_i32 v14, v0, 0, 16
	v_mul_lo_u32 v3, v3, s42
	v_add_u32_e32 v2, v13, v14
	s_add_i32 s5, s4, 0
	s_ashr_i32 s43, s42, 31
	v_add_lshl_u32 v0, v3, v2, 1
	s_add_i32 m0, s5, 0x10000
	s_ashr_i32 s44, s8, 8
	s_lshl_b64 s[26:27], s[42:43], 8
	global_load_lds_dwordx4 v0, s[10:11]
	s_add_i32 m0, s5, 0x12000
	s_add_u32 s18, s10, s26
	global_load_lds_dwordx4 v142, s[10:11]
	s_addc_u32 s19, s11, s27
	s_add_i32 m0, s5, 0x14000
	v_mov_b32_e32 v143, v1
	global_load_lds_dwordx4 v0, s[18:19]
	s_add_i32 m0, s5, 0x16000
	v_mul_lo_u32 v15, v5, s42
	v_lshl_add_u64 v[6:7], s[18:19], 0, v[0:1]
	v_lshl_add_u64 v[8:9], s[18:19], 0, v[142:143]
	global_load_lds_dwordx4 v142, s[18:19]
	s_add_i32 s18, s5, 0x2000
	v_add_lshl_u32 v146, v2, v15, 1
	s_mov_b32 m0, s5
	s_add_u32 s38, s2, s26
	global_load_lds_dwordx4 v146, s[2:3]
	s_mov_b32 m0, s18
	s_addc_u32 s39, s3, s27
	s_add_i32 s19, s5, 0x4000
	global_load_lds_dwordx4 v144, s[2:3]
	s_mov_b32 m0, s19
	s_add_i32 s20, s5, 0x6000
	global_load_lds_dwordx4 v146, s[38:39]
	s_mov_b32 m0, s20
	s_cmp_eq_u32 s44, 1
	global_load_lds_dwordx4 v144, s[38:39]
	v_lshl_add_u64 v[2:3], s[10:11], 0, v[0:1]
	v_lshl_add_u64 v[4:5], s[10:11], 0, v[142:143]
	s_cselect_b64 s[38:39], -1, 0
	s_cmp_lg_u32 s44, 1
	s_cbranch_scc1 .LBB0_411
	s_barrier

; __device__ __forceinline__ unsigned cvt_pk_bf16(float lo, float hi) { unsigned r; asm volatile("v_cvt_pk_bf16_f32 %0, %1, %2" : "=v"(r) : "v"(lo), "v"(hi)); return r; }
; #define PG8_OPQ(p) asm volatile("" : "+v"(p))
;     __device__ __forceinline__ void operator()(const f32x4 (&acc)[2][2][4][2], const Unit& u, int wr, int wc, int fr, int fq) const {
;         char* p = (char*)(O + (size_t)(wr * 64 + fr) * ldc + u.pn * BM + wc * 32 + 8 * fq);
;         const size_t step = (size_t)16 * ldc * 2;
; #pragma unroll
;         for (int ai = 0; ai < 2; ++ai) {
; #pragma unroll
;             for (int m = 0; m < 4; ++m) {
;                 PG8_OPQ(p);
; #pragma unroll
;                 for (int bj = 0; bj < 2; ++bj) { f32x4 v0 = acc[ai][bj][m][0], v1 = acc[ai][bj][m][1];
;                     if (ACT == 1) {
; #pragma unroll
;                         for (int j = 0; j < 4; ++j) { const float a0 = fmaxf(v0[j], 0.f), a1 = fmaxf(v1[j], 0.f); v0[j] = a0 * a0; v1[j] = a1 * a1; } }
;                     u32x4 w; w.x = cvt_pk_bf16(v0[0], v0[1]); w.y = cvt_pk_bf16(v0[2], v0[3]); w.z = cvt_pk_bf16(v1[0], v1[1]); w.w = cvt_pk_bf16(v1[2], v1[3]);
;                     *(u32x4*)(p + bj * HALF * 2) = w; }
;                 p += step;
;             }
;             p += 4 * step;
.LBB0_438:
	v_max_f32_e32 v122, v122, v122
	s_lshr_b32 s36, s8, 2
	s_lshl_b32 s36, s36, 23
	s_and_b32 s99, s8, 3
	s_lshl_b32 s99, s99, 8
	s_add_u32 s36, s36, s99
	s_lshr_b32 s99, s98, 14
	s_add_u32 s36, s36, s99
	v_max_f32_e32 v122, 0, v122
	v_max_f32_e32 v123, v123, v123
	v_max_f32_e32 v124, v124, v124
	v_max_f32_e32 v125, v125, v125
	v_lshl_add_u64 v[144:145], s[36:37], 1, v[136:137]
	v_max_f32_e32 v126, v126, v126
	v_mul_f32_e32 v122, v122, v122
	v_max_f32_e32 v123, 0, v123
	v_max_f32_e32 v127, v127, v127
	v_max_f32_e32 v124, 0, v124
	v_max_f32_e32 v128, v128, v128
	v_max_f32_e32 v125, 0, v125
	v_max_f32_e32 v129, v129, v129
	v_max_f32_e32 v114, v114, v114
	v_max_f32_e32 v115, v115, v115
	v_max_f32_e32 v116, v116, v116
	v_max_f32_e32 v126, 0, v126
	v_max_f32_e32 v127, 0, v127
	v_mul_f32_e32 v123, v123, v123
	v_max_f32_e32 v128, 0, v128
	v_mul_f32_e32 v124, v124, v124
	v_max_f32_e32 v129, 0, v129
	v_mul_f32_e32 v125, v125, v125
	v_cvt_pk_bf16_f32 v122, v122, v123
	v_max_f32_e32 v114, 0, v114
	v_max_f32_e32 v115, 0, v115
	v_max_f32_e32 v116, 0, v116
	v_mul_f32_e32 v126, v126, v126
	v_mul_f32_e32 v127, v127, v127
	v_mul_f32_e32 v128, v128, v128
	v_mul_f32_e32 v129, v129, v129
	v_cvt_pk_bf16_f32 v123, v124, v125
	v_cvt_pk_bf16_f32 v124, v126, v127
	v_cvt_pk_bf16_f32 v125, v128, v129
	global_store_dwordx4 v[144:145], v[122:125], off
	v_max_f32_e32 v118, v118, v118
	v_max_f32_e32 v117, v117, v117
	v_mul_f32_e32 v122, v114, v114
	v_max_f32_e32 v114, v119, v119
	v_mul_f32_e32 v119, v115, v115
	v_max_f32_e32 v115, v120, v120
	v_mul_f32_e32 v120, v116, v116
	v_max_f32_e32 v116, v121, v121
	v_max_f32_e32 v114, 0, v114
	v_max_f32_e32 v115, 0, v115
	v_max_f32_e32 v116, 0, v116
	v_max_f32_e32 v118, 0, v118
	v_mul_f32_e32 v114, v114, v114
	v_mul_f32_e32 v115, v115, v115
	v_max_f32_e32 v117, 0, v117
	v_mul_f32_e32 v116, v116, v116
	v_max_f32_e32 v106, v106, v106
	v_mul_f32_e32 v118, v118, v118
	v_mul_f32_e32 v117, v117, v117
	v_cvt_pk_bf16_f32 v114, v118, v114
	v_cvt_pk_bf16_f32 v115, v115, v116
	v_cvt_pk_bf16_f32 v116, v122, v119
	v_max_f32_e32 v106, 0, v106
	v_max_f32_e32 v107, v107, v107
	v_max_f32_e32 v108, v108, v108
	v_cvt_pk_bf16_f32 v117, v120, v117
	global_store_dwordx4 v[144:145], v[114:117], off offset:256
	v_max_f32_e32 v107, 0, v107
	v_max_f32_e32 v108, 0, v108
	v_mul_f32_e32 v116, v106, v106
	v_max_f32_e32 v106, v111, v111
	v_max_f32_e32 v110, v110, v110
	v_max_f32_e32 v106, 0, v106
	v_mul_f32_e32 v111, v107, v107
	v_max_f32_e32 v107, v112, v112
	v_mul_f32_e32 v112, v108, v108
	v_max_f32_e32 v108, v113, v113
	v_max_f32_e32 v109, v109, v109
	v_lshl_add_u64 v[114:115], v[144:145], 0, s[16:17]
	v_max_f32_e32 v110, 0, v110
	v_mul_f32_e32 v106, v106, v106
	v_max_f32_e32 v107, 0, v107
	v_max_f32_e32 v108, 0, v108
	v_max_f32_e32 v109, 0, v109
	v_max_f32_e32 v98, v98, v98
	v_max_f32_e32 v99, v99, v99
	v_max_f32_e32 v100, v100, v100
	v_mul_f32_e32 v110, v110, v110
	v_mul_f32_e32 v107, v107, v107
	v_mul_f32_e32 v108, v108, v108
	v_mul_f32_e32 v109, v109, v109
	v_cvt_pk_bf16_f32 v106, v110, v106
	v_max_f32_e32 v98, 0, v98
	v_max_f32_e32 v99, 0, v99
	v_max_f32_e32 v100, 0, v100
	v_cvt_pk_bf16_f32 v107, v107, v108
	v_cvt_pk_bf16_f32 v108, v116, v111
	v_cvt_pk_bf16_f32 v109, v112, v109
	global_store_dwordx4 v[114:115], v[106:109], off
	v_max_f32_e32 v102, v102, v102
	v_max_f32_e32 v101, v101, v101
	v_mul_f32_e32 v106, v98, v98
	v_max_f32_e32 v98, v103, v103
	v_mul_f32_e32 v103, v99, v99
	v_max_f32_e32 v99, v104, v104
	v_mul_f32_e32 v104, v100, v100
	v_max_f32_e32 v100, v105, v105
	v_max_f32_e32 v98, 0, v98
	v_max_f32_e32 v99, 0, v99
	v_max_f32_e32 v100, 0, v100
	v_max_f32_e32 v102, 0, v102
	v_mul_f32_e32 v98, v98, v98
	v_mul_f32_e32 v99, v99, v99
	v_max_f32_e32 v101, 0, v101
	v_mul_f32_e32 v100, v100, v100
	v_max_f32_e32 v90, v90, v90
	v_mul_f32_e32 v102, v102, v102
	v_mul_f32_e32 v101, v101, v101
	v_cvt_pk_bf16_f32 v98, v102, v98
	v_cvt_pk_bf16_f32 v99, v99, v100
	v_cvt_pk_bf16_f32 v100, v106, v103
	v_max_f32_e32 v90, 0, v90
	v_max_f32_e32 v91, v91, v91
	v_max_f32_e32 v92, v92, v92
	v_cvt_pk_bf16_f32 v101, v104, v101
	global_store_dwordx4 v[114:115], v[98:101], off offset:256
	v_max_f32_e32 v91, 0, v91
	v_max_f32_e32 v92, 0, v92
	v_mul_f32_e32 v100, v90, v90
	v_max_f32_e32 v90, v95, v95
	v_max_f32_e32 v94, v94, v94
	v_max_f32_e32 v90, 0, v90
	v_mul_f32_e32 v95, v91, v91
	v_max_f32_e32 v91, v96, v96
	v_mul_f32_e32 v96, v92, v92
	v_max_f32_e32 v92, v97, v97
	v_max_f32_e32 v93, v93, v93
	v_lshl_add_u64 v[98:99], v[114:115], 0, s[16:17]
	v_max_f32_e32 v94, 0, v94
	v_mul_f32_e32 v90, v90, v90
	v_max_f32_e32 v91, 0, v91
	v_max_f32_e32 v92, 0, v92
	v_max_f32_e32 v93, 0, v93
	v_max_f32_e32 v82, v82, v82
	v_max_f32_e32 v83, v83, v83
	v_max_f32_e32 v84, v84, v84
	v_mul_f32_e32 v94, v94, v94
	v_mul_f32_e32 v91, v91, v91
	v_mul_f32_e32 v92, v92, v92
	v_mul_f32_e32 v93, v93, v93
	v_cvt_pk_bf16_f32 v90, v94, v90
	v_max_f32_e32 v82, 0, v82
	v_max_f32_e32 v83, 0, v83
	v_max_f32_e32 v84, 0, v84
	v_cvt_pk_bf16_f32 v91, v91, v92
	v_cvt_pk_bf16_f32 v92, v100, v95
	v_cvt_pk_bf16_f32 v93, v96, v93
	global_store_dwordx4 v[98:99], v[90:93], off
	v_max_f32_e32 v86, v86, v86
	v_max_f32_e32 v85, v85, v85
	v_mul_f32_e32 v90, v82, v82
	v_max_f32_e32 v82, v87, v87
	v_mul_f32_e32 v87, v83, v83
	v_max_f32_e32 v83, v88, v88
	v_mul_f32_e32 v88, v84, v84
	v_max_f32_e32 v84, v89, v89
	v_max_f32_e32 v82, 0, v82
	v_max_f32_e32 v83, 0, v83
	v_max_f32_e32 v84, 0, v84
	v_max_f32_e32 v86, 0, v86
	v_mul_f32_e32 v82, v82, v82
	v_mul_f32_e32 v83, v83, v83
	v_max_f32_e32 v85, 0, v85
	v_mul_f32_e32 v84, v84, v84
	v_max_f32_e32 v74, v74, v74
	v_mul_f32_e32 v86, v86, v86
	v_mul_f32_e32 v85, v85, v85
; __device__ __forceinline__ unsigned cvt_pk_bf16(float lo, float hi) { unsigned r; asm volatile("v_cvt_pk_bf16_f32 %0, %1, %2" : "=v"(r) : "v"(lo), "v"(hi)); return r; }
; #define PG8_OPQ(p) asm volatile("" : "+v"(p))
;     __device__ __forceinline__ void operator()(const f32x4 (&acc)[2][2][4][2], const Unit& u, int wr, int wc, int fr, int fq) const {
;         char* p = (char*)(O + (size_t)(wr * 64 + fr) * ldc + u.pn * BM + wc * 32 + 8 * fq);
;         const size_t step = (size_t)16 * ldc * 2;
; #pragma unroll
;         for (int ai = 0; ai < 2; ++ai) {
; #pragma unroll
;             for (int m = 0; m < 4; ++m) {
;                 PG8_OPQ(p);
; #pragma unroll
;                 for (int bj = 0; bj < 2; ++bj) { f32x4 v0 = acc[ai][bj][m][0], v1 = acc[ai][bj][m][1];
;                     if (ACT == 1) {
; #pragma unroll
;                         for (int j = 0; j < 4; ++j) { const float a0 = fmaxf(v0[j], 0.f), a1 = fmaxf(v1[j], 0.f); v0[j] = a0 * a0; v1[j] = a1 * a1; } }
;                     u32x4 w; w.x = cvt_pk_bf16(v0[0], v0[1]); w.y = cvt_pk_bf16(v0[2], v0[3]); w.z = cvt_pk_bf16(v1[0], v1[1]); w.w = cvt_pk_bf16(v1[2], v1[3]);
;                     *(u32x4*)(p + bj * HALF * 2) = w; }
;                 p += step;
;             }
;             p += 4 * step;
	v_cvt_pk_bf16_f32 v82, v86, v82
	v_cvt_pk_bf16_f32 v83, v83, v84
	v_cvt_pk_bf16_f32 v84, v90, v87
	v_max_f32_e32 v74, 0, v74
	v_max_f32_e32 v75, v75, v75
	v_max_f32_e32 v76, v76, v76
	v_cvt_pk_bf16_f32 v85, v88, v85
	global_store_dwordx4 v[98:99], v[82:85], off offset:256
	v_max_f32_e32 v75, 0, v75
	v_max_f32_e32 v76, 0, v76
	v_mul_f32_e32 v84, v74, v74
	v_max_f32_e32 v74, v79, v79
	v_max_f32_e32 v78, v78, v78
	v_max_f32_e32 v74, 0, v74
	v_mul_f32_e32 v79, v75, v75
	v_max_f32_e32 v75, v80, v80
	v_mul_f32_e32 v80, v76, v76
	v_max_f32_e32 v76, v81, v81
	v_max_f32_e32 v77, v77, v77
	v_lshl_add_u64 v[82:83], v[98:99], 0, s[16:17]
	v_max_f32_e32 v78, 0, v78
	v_mul_f32_e32 v74, v74, v74
	v_max_f32_e32 v75, 0, v75
	v_max_f32_e32 v76, 0, v76
	v_max_f32_e32 v77, 0, v77
	v_max_f32_e32 v66, v66, v66
	v_max_f32_e32 v67, v67, v67
	v_max_f32_e32 v68, v68, v68
	v_mul_f32_e32 v78, v78, v78
	v_mul_f32_e32 v75, v75, v75
	v_mul_f32_e32 v76, v76, v76
	v_mul_f32_e32 v77, v77, v77
	v_cvt_pk_bf16_f32 v74, v78, v74
	v_max_f32_e32 v66, 0, v66
	v_max_f32_e32 v67, 0, v67
	v_max_f32_e32 v68, 0, v68
	v_cvt_pk_bf16_f32 v75, v75, v76
	v_cvt_pk_bf16_f32 v76, v84, v79
	v_cvt_pk_bf16_f32 v77, v80, v77
	global_store_dwordx4 v[82:83], v[74:77], off
	v_max_f32_e32 v70, v70, v70
	v_max_f32_e32 v69, v69, v69
	v_mul_f32_e32 v74, v66, v66
	v_max_f32_e32 v66, v71, v71
	v_mul_f32_e32 v71, v67, v67
	v_max_f32_e32 v67, v72, v72
	v_mul_f32_e32 v72, v68, v68
	v_max_f32_e32 v68, v73, v73
	v_max_f32_e32 v66, 0, v66
	v_max_f32_e32 v67, 0, v67
	v_max_f32_e32 v68, 0, v68
	v_max_f32_e32 v70, 0, v70
	v_mul_f32_e32 v66, v66, v66
	v_mul_f32_e32 v67, v67, v67
	v_max_f32_e32 v69, 0, v69
	v_mul_f32_e32 v68, v68, v68
	v_max_f32_e32 v58, v58, v58
	v_mul_f32_e32 v70, v70, v70
	v_mul_f32_e32 v69, v69, v69
	v_cvt_pk_bf16_f32 v66, v70, v66
	v_cvt_pk_bf16_f32 v67, v67, v68
	v_cvt_pk_bf16_f32 v68, v74, v71
	v_max_f32_e32 v58, 0, v58
	v_max_f32_e32 v59, v59, v59
	v_max_f32_e32 v60, v60, v60
	v_cvt_pk_bf16_f32 v69, v72, v69
	global_store_dwordx4 v[82:83], v[66:69], off offset:256
	v_max_f32_e32 v59, 0, v59
	v_max_f32_e32 v60, 0, v60
	v_mul_f32_e32 v68, v58, v58
	v_max_f32_e32 v58, v63, v63
	s_mov_b64 s[48:49], 0xa0000
	v_max_f32_e32 v62, v62, v62
	v_max_f32_e32 v58, 0, v58
	v_mul_f32_e32 v63, v59, v59
	v_max_f32_e32 v59, v64, v64
	v_mul_f32_e32 v64, v60, v60
	v_max_f32_e32 v60, v65, v65
	v_max_f32_e32 v61, v61, v61
	v_lshl_add_u64 v[66:67], v[82:83], 0, s[48:49]
	v_max_f32_e32 v62, 0, v62
	v_mul_f32_e32 v58, v58, v58
	v_max_f32_e32 v59, 0, v59
	v_max_f32_e32 v60, 0, v60
	v_max_f32_e32 v61, 0, v61
	v_max_f32_e32 v50, v50, v50
	v_max_f32_e32 v51, v51, v51
	v_max_f32_e32 v52, v52, v52
	v_mul_f32_e32 v62, v62, v62
	v_mul_f32_e32 v59, v59, v59
	v_mul_f32_e32 v60, v60, v60
	v_mul_f32_e32 v61, v61, v61
	v_cvt_pk_bf16_f32 v58, v62, v58
	v_max_f32_e32 v50, 0, v50
	v_max_f32_e32 v51, 0, v51
	v_max_f32_e32 v52, 0, v52
	v_cvt_pk_bf16_f32 v59, v59, v60
	v_cvt_pk_bf16_f32 v60, v68, v63
	v_cvt_pk_bf16_f32 v61, v64, v61
	global_store_dwordx4 v[66:67], v[58:61], off
	v_max_f32_e32 v54, v54, v54
	v_max_f32_e32 v53, v53, v53
	v_mul_f32_e32 v58, v50, v50
	v_max_f32_e32 v50, v55, v55
	v_mul_f32_e32 v55, v51, v51
	v_max_f32_e32 v51, v56, v56
	v_mul_f32_e32 v56, v52, v52
	v_max_f32_e32 v52, v57, v57
	v_max_f32_e32 v50, 0, v50
	v_max_f32_e32 v51, 0, v51
	v_max_f32_e32 v52, 0, v52
	v_max_f32_e32 v54, 0, v54
	v_mul_f32_e32 v50, v50, v50
	v_mul_f32_e32 v51, v51, v51
	v_max_f32_e32 v53, 0, v53
	v_mul_f32_e32 v52, v52, v52
	v_max_f32_e32 v42, v42, v42
	v_mul_f32_e32 v54, v54, v54
	v_mul_f32_e32 v53, v53, v53
	v_cvt_pk_bf16_f32 v50, v54, v50
	v_cvt_pk_bf16_f32 v51, v51, v52
	v_cvt_pk_bf16_f32 v52, v58, v55
	v_max_f32_e32 v42, 0, v42
	v_max_f32_e32 v43, v43, v43
	v_max_f32_e32 v44, v44, v44
	v_cvt_pk_bf16_f32 v53, v56, v53
	global_store_dwordx4 v[66:67], v[50:53], off offset:256
	v_max_f32_e32 v43, 0, v43
	v_max_f32_e32 v44, 0, v44
	v_mul_f32_e32 v52, v42, v42
	v_max_f32_e32 v42, v47, v47
	v_max_f32_e32 v46, v46, v46
	v_max_f32_e32 v42, 0, v42
	v_mul_f32_e32 v47, v43, v43
	v_max_f32_e32 v43, v48, v48
	v_mul_f32_e32 v48, v44, v44
	v_max_f32_e32 v44, v49, v49
	v_max_f32_e32 v45, v45, v45
	v_lshl_add_u64 v[50:51], v[66:67], 0, s[16:17]
	v_max_f32_e32 v46, 0, v46
	v_mul_f32_e32 v42, v42, v42
	v_max_f32_e32 v43, 0, v43
	v_max_f32_e32 v44, 0, v44
	v_max_f32_e32 v45, 0, v45
	v_max_f32_e32 v34, v34, v34
	v_max_f32_e32 v35, v35, v35
	v_max_f32_e32 v36, v36, v36
	v_mul_f32_e32 v46, v46, v46
	v_mul_f32_e32 v43, v43, v43
	v_mul_f32_e32 v44, v44, v44
	v_mul_f32_e32 v45, v45, v45
	v_cvt_pk_bf16_f32 v42, v46, v42
; __device__ __forceinline__ unsigned cvt_pk_bf16(float lo, float hi) { unsigned r; asm volatile("v_cvt_pk_bf16_f32 %0, %1, %2" : "=v"(r) : "v"(lo), "v"(hi)); return r; }
; #define PG8_BAR __builtin_amdgcn_s_barrier()
; #define PG8_OPQ(p) asm volatile("" : "+v"(p))
; template <class Epi, class Sched>
; __device__ __forceinline__ void gemm_phase(LAS unsigned char* lds, const Gemm g, const Sched& S, const Epi& E) {
;     ...
;         if (!has_next) break;
; #pragma unroll
;         for (int a = 0; a < 2; ++a)
; #pragma unroll
;             for (int b = 0; b < 2; ++b)
; #pragma unroll
;                 for (int m = 0; m < 4; ++m)
; #pragma unroll
;                     for (int n = 0; n < 2; ++n) acc[a][b][m][n] = (f32x4){0.f, 0.f, 0.f, 0.f};
;         cur = nxt; cA = nA; cB = nB; ++ui;
;         if (wr == 1) PG8_BAR;
;     __device__ __forceinline__ void operator()(const f32x4 (&acc)[2][2][4][2], const Unit& u, int wr, int wc, int fr, int fq) const {
;     ...
;             for (int m = 0; m < 4; ++m) {
;                 PG8_OPQ(p);
; #pragma unroll
;                 for (int bj = 0; bj < 2; ++bj) { f32x4 v0 = acc[ai][bj][m][0], v1 = acc[ai][bj][m][1];
;                     if (ACT == 1) {
; #pragma unroll
;                         for (int j = 0; j < 4; ++j) { const float a0 = fmaxf(v0[j], 0.f), a1 = fmaxf(v1[j], 0.f); v0[j] = a0 * a0; v1[j] = a1 * a1; } }
;                     u32x4 w; w.x = cvt_pk_bf16(v0[0], v0[1]); w.y = cvt_pk_bf16(v0[2], v0[3]); w.z = cvt_pk_bf16(v1[0], v1[1]); w.w = cvt_pk_bf16(v1[2], v1[3]);
;                     *(u32x4*)(p + bj * HALF * 2) = w; }
;                 p += step;
;             }
;             p += 4 * step;
	v_max_f32_e32 v34, 0, v34
	v_max_f32_e32 v35, 0, v35
	v_max_f32_e32 v36, 0, v36
	v_cvt_pk_bf16_f32 v43, v43, v44
	v_cvt_pk_bf16_f32 v44, v52, v47
	v_cvt_pk_bf16_f32 v45, v48, v45
	global_store_dwordx4 v[50:51], v[42:45], off
	v_max_f32_e32 v38, v38, v38
	v_max_f32_e32 v37, v37, v37
	v_mul_f32_e32 v42, v34, v34
	v_max_f32_e32 v34, v39, v39
	v_mul_f32_e32 v39, v35, v35
	v_max_f32_e32 v35, v40, v40
	v_mul_f32_e32 v40, v36, v36
	v_max_f32_e32 v36, v41, v41
	v_max_f32_e32 v34, 0, v34
	v_max_f32_e32 v35, 0, v35
	v_max_f32_e32 v36, 0, v36
	v_max_f32_e32 v38, 0, v38
	v_mul_f32_e32 v34, v34, v34
	v_mul_f32_e32 v35, v35, v35
	v_max_f32_e32 v37, 0, v37
	v_mul_f32_e32 v36, v36, v36
	v_max_f32_e32 v26, v26, v26
	v_mul_f32_e32 v38, v38, v38
	v_mul_f32_e32 v37, v37, v37
	v_cvt_pk_bf16_f32 v34, v38, v34
	v_cvt_pk_bf16_f32 v35, v35, v36
	v_cvt_pk_bf16_f32 v36, v42, v39
	v_max_f32_e32 v26, 0, v26
	v_max_f32_e32 v27, v27, v27
	v_max_f32_e32 v28, v28, v28
	v_cvt_pk_bf16_f32 v37, v40, v37
	global_store_dwordx4 v[50:51], v[34:37], off offset:256
	v_max_f32_e32 v27, 0, v27
	v_max_f32_e32 v28, 0, v28
	v_mul_f32_e32 v36, v26, v26
	v_max_f32_e32 v26, v31, v31
	v_max_f32_e32 v30, v30, v30
	v_max_f32_e32 v26, 0, v26
	v_mul_f32_e32 v31, v27, v27
	v_max_f32_e32 v27, v32, v32
	v_mul_f32_e32 v32, v28, v28
	v_max_f32_e32 v28, v33, v33
	v_max_f32_e32 v29, v29, v29
	v_lshl_add_u64 v[34:35], v[50:51], 0, s[16:17]
	v_max_f32_e32 v30, 0, v30
	v_mul_f32_e32 v26, v26, v26
	v_max_f32_e32 v27, 0, v27
	v_max_f32_e32 v28, 0, v28
	v_max_f32_e32 v29, 0, v29
	v_max_f32_e32 v18, v18, v18
	v_max_f32_e32 v19, v19, v19
	v_max_f32_e32 v20, v20, v20
	v_mul_f32_e32 v30, v30, v30
	v_mul_f32_e32 v27, v27, v27
	v_mul_f32_e32 v28, v28, v28
	v_mul_f32_e32 v29, v29, v29
	v_cvt_pk_bf16_f32 v26, v30, v26
	v_max_f32_e32 v18, 0, v18
	v_max_f32_e32 v19, 0, v19
	v_max_f32_e32 v20, 0, v20
	v_cvt_pk_bf16_f32 v27, v27, v28
	v_cvt_pk_bf16_f32 v28, v36, v31
	v_cvt_pk_bf16_f32 v29, v32, v29
	global_store_dwordx4 v[34:35], v[26:29], off
	v_max_f32_e32 v22, v22, v22
	v_max_f32_e32 v21, v21, v21
	v_mul_f32_e32 v26, v18, v18
	v_max_f32_e32 v18, v23, v23
	v_mul_f32_e32 v23, v19, v19
	v_max_f32_e32 v19, v24, v24
	v_mul_f32_e32 v24, v20, v20
	v_max_f32_e32 v20, v25, v25
	v_max_f32_e32 v18, 0, v18
	v_max_f32_e32 v19, 0, v19
	v_max_f32_e32 v20, 0, v20
	v_max_f32_e32 v22, 0, v22
	v_mul_f32_e32 v18, v18, v18
	v_mul_f32_e32 v19, v19, v19
	v_max_f32_e32 v21, 0, v21
	v_mul_f32_e32 v20, v20, v20
	v_max_f32_e32 v10, v10, v10
	v_mul_f32_e32 v22, v22, v22
	v_mul_f32_e32 v21, v21, v21
	v_cvt_pk_bf16_f32 v18, v22, v18
	v_cvt_pk_bf16_f32 v19, v19, v20
	v_cvt_pk_bf16_f32 v20, v26, v23
	v_max_f32_e32 v10, 0, v10
	v_max_f32_e32 v11, v11, v11
	v_max_f32_e32 v12, v12, v12
	v_cvt_pk_bf16_f32 v21, v24, v21
	global_store_dwordx4 v[34:35], v[18:21], off offset:256
	v_max_f32_e32 v11, 0, v11
	v_max_f32_e32 v12, 0, v12
	v_mul_f32_e32 v20, v10, v10
	v_max_f32_e32 v10, v15, v15
	v_max_f32_e32 v14, v14, v14
	v_max_f32_e32 v10, 0, v10
	v_mul_f32_e32 v15, v11, v11
	v_max_f32_e32 v11, v16, v16
	v_mul_f32_e32 v16, v12, v12
	v_max_f32_e32 v12, v17, v17
	v_max_f32_e32 v13, v13, v13
	v_lshl_add_u64 v[18:19], v[34:35], 0, s[16:17]
	v_max_f32_e32 v14, 0, v14
	v_mul_f32_e32 v10, v10, v10
	v_max_f32_e32 v11, 0, v11
	v_max_f32_e32 v12, 0, v12
	v_max_f32_e32 v13, 0, v13
	v_max_f32_e32 v2, v2, v2
	v_max_f32_e32 v3, v3, v3
	v_max_f32_e32 v4, v4, v4
	v_mul_f32_e32 v14, v14, v14
	v_mul_f32_e32 v11, v11, v11
	v_mul_f32_e32 v12, v12, v12
	v_mul_f32_e32 v13, v13, v13
	v_cvt_pk_bf16_f32 v10, v14, v10
	v_max_f32_e32 v2, 0, v2
	v_max_f32_e32 v3, 0, v3
	v_max_f32_e32 v4, 0, v4
	v_cvt_pk_bf16_f32 v11, v11, v12
	v_cvt_pk_bf16_f32 v12, v20, v15
	v_cvt_pk_bf16_f32 v13, v16, v13
	global_store_dwordx4 v[18:19], v[10:13], off
	v_max_f32_e32 v5, v5, v5
	v_max_f32_e32 v6, v6, v6
	v_mul_f32_e32 v10, v2, v2
	v_max_f32_e32 v2, v7, v7
	v_mul_f32_e32 v7, v3, v3
	v_max_f32_e32 v3, v8, v8
	v_mul_f32_e32 v8, v4, v4
	v_max_f32_e32 v4, v9, v9
	v_max_f32_e32 v2, 0, v2
	v_max_f32_e32 v3, 0, v3
	v_max_f32_e32 v4, 0, v4
	v_max_f32_e32 v5, 0, v5
	v_max_f32_e32 v6, 0, v6
	v_mul_f32_e32 v2, v2, v2
	v_mul_f32_e32 v3, v3, v3
	v_mul_f32_e32 v4, v4, v4
	v_mul_f32_e32 v5, v5, v5
	s_cmp_eq_u32 s8, 15
	s_mov_b64 s[8:9], -1
	v_mul_f32_e32 v6, v6, v6
	v_cvt_pk_bf16_f32 v2, v6, v2
	v_cvt_pk_bf16_f32 v3, v3, v4
	v_cvt_pk_bf16_f32 v4, v10, v7
	v_cvt_pk_bf16_f32 v5, v8, v5
	global_store_dwordx4 v[18:19], v[2:5], off offset:256
	s_cbranch_scc1 .LBB0_430
	s_andn2_b64 vcc, exec, s[38:39]
	s_cbranch_vccnz .LBB0_429
	s_barrier
	s_branch .LBB0_429
